# PEER up: gather addresses via 32-bit add + SGPR-base loads instead of 64-bit v_lshl_add_u64 per expert row
# speedup vs baseline: 1.0173x; 1.0013x over previous
; DI void peer_up_phase(const Params& p, unsigned char* smem, int layer, u32* ctr) {
;     ...
;   for (int si = 0; si < (stat ? 1 : 8); ++si) {
;     const int slice = stat ? xi : ((xcc + si) & 7);
;     for (;;) {
;       int item;
;       if (stat) { item = it_next; it_next += it_step; }
;       else {
;         __syncthreads();
;         if (tid == 0) *slot = (int)atomicAdd(ctr + slice, 1u);
;         __syncthreads();
;         item = *slot;
;       }
;       if (item >= 256) break;
;       const int t0 = item * 64 + 16 * w;
;       const unsigned char* wbase = wu + slice * 128 + c * 16;
.LBB0_813:
	s_add_i32 s6, s31, s4
	s_and_b32 s6, s6, 7
	v_mov_b32_e32 v4, s6
	v_cndmask_b32_e64 v4, v2, v4, s[10:11]
	s_lshl_b32 s6, s6, 2
	v_lshlrev_b32_e32 v4, 7, v4
	s_add_u32 s42, s5, s6
	v_ashrrev_i32_e32 v5, 31, v4
	s_addc_u32 s43, s30, 0
	v_lshl_add_u64 v[174:175], v[134:135], 0, v[4:5]
	s_nop 0
	v_readfirstlane_b32 s98, v174
	v_readfirstlane_b32 s99, v175
	v_and_b32_e32 v250, 7, v160
	v_lshlrev_b32_e32 v250, 4, v250
	v_lshl_add_u64 v[176:177], v[4:5], 2, v[136:137]
	v_mov_b32_e32 v4, v0
	s_branch .LBB0_816

; DI void up_issue(u32x4 (&W)[16], u32 (&pj)[16], const u32* pl, const unsigned char* wbase, int grp) {
; #pragma unroll
;   for (int j = 0; j < 16; ++j) {
;     pj[j] = pl[8 * j + grp];
;     W[j] = *(const u32x4*)(wbase + (size_t)(pj[j] >> 16) * 1024);
;   }
; DI void peer_up_phase(const Params& p, unsigned char* smem, int layer, u32* ctr) {
;     ...
;       const int t0 = item * 64 + 16 * w;
;       const unsigned char* wbase = wu + slice * 128 + c * 16;
;       {
;         const u32* src = hgp + (size_t)t0 * 128;
; #pragma unroll
;         for (int i = 0; i < 32; ++i) pl[i * 64 + lane] = src[i * 64 + lane];
;       }
;       float* ybase = yb + (size_t)t0 * 1024 + slice * 128;
;       u32x4 WA[16], WB[16];
;       u32 pA[16], pB[16];
;       up_issue(WA, pA, pl, wbase, grp);
.LBB0_824:
	v_cmp_lt_i32_e32 vcc, s48, v4
	s_mov_b64 s[28:29], -1
	s_cbranch_vccnz .LBB0_815
	s_waitcnt vmcnt(3)
	v_lshl_add_u32 v68, v4, 6, v3
	v_ashrrev_i32_e32 v69, 31, v68
	v_lshlrev_b64 v[4:5], 9, v[68:69]
	v_lshl_add_u64 v[4:5], s[38:39], 0, v[4:5]
	v_mov_b32_e32 v139, v133
	v_lshl_add_u64 v[6:7], v[4:5], 0, v[138:139]
	global_load_dword v38, v[6:7], off
	global_load_dword v39, v[6:7], off offset:256
	v_mov_b32_e32 v141, v133
	v_mov_b32_e32 v143, v133
	v_mov_b32_e32 v145, v133
	v_mov_b32_e32 v147, v133
	v_mov_b32_e32 v149, v133
	v_mov_b32_e32 v151, v133
	v_mov_b32_e32 v153, v133
	v_mov_b32_e32 v155, v133
	v_mov_b32_e32 v157, v133
	v_mov_b32_e32 v159, v133
	v_mov_b32_e32 v163, v133
	v_mov_b32_e32 v165, v133
	v_mov_b32_e32 v167, v133
	v_mov_b32_e32 v169, v133
	v_mov_b32_e32 v171, v133
	v_mov_b32_e32 v173, v133
	v_lshl_add_u64 v[8:9], v[4:5], 0, v[140:141]
	v_lshl_add_u64 v[10:11], v[4:5], 0, v[142:143]
	v_lshl_add_u64 v[12:13], v[4:5], 0, v[144:145]
	v_lshl_add_u64 v[14:15], v[4:5], 0, v[146:147]
	v_lshl_add_u64 v[16:17], v[4:5], 0, v[148:149]
	v_lshl_add_u64 v[18:19], v[4:5], 0, v[150:151]
	v_lshl_add_u64 v[20:21], v[4:5], 0, v[152:153]
	v_lshl_add_u64 v[22:23], v[4:5], 0, v[154:155]
	v_lshl_add_u64 v[24:25], v[4:5], 0, v[156:157]
	v_lshl_add_u64 v[26:27], v[4:5], 0, v[158:159]
	v_lshl_add_u64 v[28:29], v[4:5], 0, v[162:163]
	v_lshl_add_u64 v[30:31], v[4:5], 0, v[164:165]
	v_lshl_add_u64 v[32:33], v[4:5], 0, v[166:167]
	v_lshl_add_u64 v[34:35], v[4:5], 0, v[168:169]
	v_lshl_add_u64 v[36:37], v[4:5], 0, v[170:171]
	v_lshl_add_u64 v[4:5], v[4:5], 0, v[172:173]
	global_load_dword v70, v[6:7], off offset:512
	global_load_dword v71, v[6:7], off offset:768
	global_load_dword v72, v[6:7], off offset:1024
	global_load_dword v73, v[6:7], off offset:1280
	global_load_dword v74, v[6:7], off offset:1536
	global_load_dword v75, v[6:7], off offset:1792
	global_load_dword v76, v[6:7], off offset:2048
	global_load_dword v77, v[6:7], off offset:2304
	global_load_dword v78, v[6:7], off offset:2560
	global_load_dword v79, v[6:7], off offset:2816
	global_load_dword v80, v[6:7], off offset:3072
	global_load_dword v81, v[6:7], off offset:3328
	global_load_dword v82, v[6:7], off offset:3584
	global_load_dword v83, v[6:7], off offset:3840
	global_load_dword v84, v[8:9], off
	global_load_dword v85, v[10:11], off
	global_load_dword v86, v[12:13], off
	global_load_dword v87, v[14:15], off
	global_load_dword v88, v[16:17], off
	global_load_dword v89, v[18:19], off
	global_load_dword v90, v[20:21], off
	global_load_dword v91, v[22:23], off
	global_load_dword v92, v[24:25], off
	global_load_dword v93, v[26:27], off
	global_load_dword v94, v[28:29], off
	global_load_dword v95, v[30:31], off
	global_load_dword v96, v[32:33], off
	global_load_dword v97, v[34:35], off
	global_load_dword v98, v[36:37], off
	global_load_dword v99, v[4:5], off
	v_cmp_lt_i32_e32 vcc, v223, v218
	v_lshlrev_b64 v[68:69], 12, v[68:69]
	s_mov_b32 s44, 0
	v_lshl_add_u64 v[188:189], v[176:177], 0, v[68:69]
	v_mov_b32_e32 v145, v214
	s_waitcnt vmcnt(30)
	ds_write2st64_b32 v213, v38, v39 offset0:1 offset1:2
	ds_read2_b32 v[178:179], v212 offset0:64 offset1:72
	ds_read2_b32 v[180:181], v212 offset0:80 offset1:88
	ds_read2_b32 v[182:183], v212 offset0:96 offset1:104
	ds_read2_b32 v[184:185], v212 offset0:112 offset1:120
	ds_read2_b32 v[186:187], v212 offset0:128 offset1:136
	s_waitcnt lgkmcnt(4)
	v_lshlrev_b32_sdwa v132, v215, v178 dst_sel:DWORD dst_unused:UNUSED_PAD src0_sel:DWORD src1_sel:WORD_1
	v_add_u32_e32 v4, v250, v132
	v_lshlrev_b32_sdwa v132, v215, v179 dst_sel:DWORD dst_unused:UNUSED_PAD src0_sel:DWORD src1_sel:WORD_1
	v_add_u32_e32 v8, v250, v132
	s_waitcnt lgkmcnt(3)
	v_lshlrev_b32_sdwa v132, v215, v180 dst_sel:DWORD dst_unused:UNUSED_PAD src0_sel:DWORD src1_sel:WORD_1
	v_add_u32_e32 v12, v250, v132
	v_lshlrev_b32_sdwa v132, v215, v181 dst_sel:DWORD dst_unused:UNUSED_PAD src0_sel:DWORD src1_sel:WORD_1
	v_add_u32_e32 v16, v250, v132
	s_waitcnt lgkmcnt(2)
; DI void up_issue(u32x4 (&W)[16], u32 (&pj)[16], const u32* pl, const unsigned char* wbase, int grp) {
; #pragma unroll
;   for (int j = 0; j < 16; ++j) {
;     pj[j] = pl[8 * j + grp];
;     W[j] = *(const u32x4*)(wbase + (size_t)(pj[j] >> 16) * 1024);
;   }
; DI void peer_up_phase(const Params& p, unsigned char* smem, int layer, u32* ctr) {
;     ...
;       {
;         const u32* src = hgp + (size_t)t0 * 128;
; #pragma unroll
;         for (int i = 0; i < 32; ++i) pl[i * 64 + lane] = src[i * 64 + lane];
;       }
	v_lshlrev_b32_sdwa v132, v215, v182 dst_sel:DWORD dst_unused:UNUSED_PAD src0_sel:DWORD src1_sel:WORD_1
	v_add_u32_e32 v20, v250, v132
	v_lshlrev_b32_sdwa v132, v215, v183 dst_sel:DWORD dst_unused:UNUSED_PAD src0_sel:DWORD src1_sel:WORD_1
	v_add_u32_e32 v24, v250, v132
	s_waitcnt lgkmcnt(1)
	v_lshlrev_b32_sdwa v132, v215, v184 dst_sel:DWORD dst_unused:UNUSED_PAD src0_sel:DWORD src1_sel:WORD_1
	v_add_u32_e32 v28, v250, v132
	v_lshlrev_b32_sdwa v132, v215, v185 dst_sel:DWORD dst_unused:UNUSED_PAD src0_sel:DWORD src1_sel:WORD_1
	v_add_u32_e32 v32, v250, v132
	global_load_dwordx4 v[4:7], v4, s[98:99]
	s_nop 0
	global_load_dwordx4 v[8:11], v8, s[98:99]
	s_nop 0
	global_load_dwordx4 v[12:15], v12, s[98:99]
	s_nop 0
	global_load_dwordx4 v[16:19], v16, s[98:99]
	s_nop 0
	global_load_dwordx4 v[20:23], v20, s[98:99]
	s_nop 0
	global_load_dwordx4 v[24:27], v24, s[98:99]
	s_nop 0
	global_load_dwordx4 v[28:31], v28, s[98:99]
	s_nop 0
	global_load_dwordx4 v[32:35], v32, s[98:99]
	ds_read2_b32 v[190:191], v212 offset0:144 offset1:152
	s_waitcnt lgkmcnt(1)
	v_lshlrev_b32_sdwa v132, v215, v186 dst_sel:DWORD dst_unused:UNUSED_PAD src0_sel:DWORD src1_sel:WORD_1
	v_add_u32_e32 v36, v250, v132
	v_lshlrev_b32_sdwa v132, v215, v187 dst_sel:DWORD dst_unused:UNUSED_PAD src0_sel:DWORD src1_sel:WORD_1
	v_add_u32_e32 v40, v250, v132
	s_waitcnt lgkmcnt(0)
	v_lshlrev_b32_sdwa v132, v215, v190 dst_sel:DWORD dst_unused:UNUSED_PAD src0_sel:DWORD src1_sel:WORD_1
	global_load_dwordx4 v[36:39], v36, s[98:99]
	s_nop 0
	global_load_dwordx4 v[40:43], v40, s[98:99]
	v_add_u32_e32 v44, v250, v132
	ds_read2_b32 v[192:193], v212 offset0:160 offset1:168
	v_lshlrev_b32_sdwa v132, v215, v191 dst_sel:DWORD dst_unused:UNUSED_PAD src0_sel:DWORD src1_sel:WORD_1
	v_add_u32_e32 v48, v250, v132
	global_load_dwordx4 v[44:47], v44, s[98:99]
	s_nop 0
	global_load_dwordx4 v[48:51], v48, s[98:99]
	ds_read2_b32 v[194:195], v212 offset0:176 offset1:184
	s_waitcnt lgkmcnt(1)
	v_lshlrev_b32_sdwa v132, v215, v192 dst_sel:DWORD dst_unused:UNUSED_PAD src0_sel:DWORD src1_sel:WORD_1
	v_add_u32_e32 v52, v250, v132
	v_lshlrev_b32_sdwa v132, v215, v193 dst_sel:DWORD dst_unused:UNUSED_PAD src0_sel:DWORD src1_sel:WORD_1
	v_add_u32_e32 v56, v250, v132
	s_waitcnt lgkmcnt(0)
	v_lshlrev_b32_sdwa v132, v215, v194 dst_sel:DWORD dst_unused:UNUSED_PAD src0_sel:DWORD src1_sel:WORD_1
	v_add_u32_e32 v60, v250, v132
	v_lshlrev_b32_sdwa v132, v215, v195 dst_sel:DWORD dst_unused:UNUSED_PAD src0_sel:DWORD src1_sel:WORD_1
	v_add_u32_e32 v64, v250, v132
	global_load_dwordx4 v[52:55], v52, s[98:99]
	s_nop 0
	global_load_dwordx4 v[56:59], v56, s[98:99]
	s_nop 0
	global_load_dwordx4 v[60:63], v60, s[98:99]
	s_nop 0
	global_load_dwordx4 v[64:67], v64, s[98:99]
	s_waitcnt vmcnt(44)
	ds_write2st64_b32 v213, v70, v71 offset0:3 offset1:4
	s_waitcnt vmcnt(42)
	ds_write2st64_b32 v213, v72, v73 offset0:5 offset1:6
	s_waitcnt vmcnt(40)
	ds_write2st64_b32 v213, v74, v75 offset0:7 offset1:8
	s_waitcnt vmcnt(38)
	ds_write2st64_b32 v213, v76, v77 offset0:9 offset1:10
	s_waitcnt vmcnt(36)
	ds_write2st64_b32 v213, v78, v79 offset0:11 offset1:12
	s_waitcnt vmcnt(34)
	ds_write2st64_b32 v213, v80, v81 offset0:13 offset1:14
	s_waitcnt vmcnt(32)
	ds_write2st64_b32 v213, v82, v83 offset0:15 offset1:16
	s_waitcnt vmcnt(30)
	ds_write2st64_b32 v213, v84, v85 offset0:17 offset1:18
	s_waitcnt vmcnt(28)
	ds_write2st64_b32 v213, v86, v87 offset0:19 offset1:20
	s_waitcnt vmcnt(26)
	ds_write2st64_b32 v213, v88, v89 offset0:21 offset1:22
	s_waitcnt vmcnt(24)
	ds_write2st64_b32 v213, v90, v91 offset0:23 offset1:24
	s_waitcnt vmcnt(22)
	ds_write2st64_b32 v213, v92, v93 offset0:25 offset1:26
	s_waitcnt vmcnt(20)
	ds_write2st64_b32 v213, v94, v95 offset0:27 offset1:28
	s_waitcnt vmcnt(18)
	ds_write2st64_b32 v213, v96, v97 offset0:29 offset1:30
	s_waitcnt vmcnt(16)
	ds_write2st64_b32 v213, v98, v99 offset0:31 offset1:32
	v_cndmask_b32_e32 v70, v161, v223, vcc
	v_cmp_lt_i32_e32 vcc, v224, v218
	v_lshlrev_b32_e32 v139, 2, v70
	s_nop 0
	v_cndmask_b32_e32 v70, v161, v224, vcc
	v_cmp_lt_i32_e32 vcc, v222, v218
	v_lshlrev_b32_e32 v141, 2, v70
	s_nop 0
	v_cndmask_b32_e32 v70, v161, v222, vcc
	v_lshlrev_b32_e32 v143, 2, v70
	s_branch .LBB0_827

; DI void up_issue(u32x4 (&W)[16], u32 (&pj)[16], const u32* pl, const unsigned char* wbase, int grp) {
; #pragma unroll
;   for (int j = 0; j < 16; ++j) {
;     pj[j] = pl[8 * j + grp];
;     W[j] = *(const u32x4*)(wbase + (size_t)(pj[j] >> 16) * 1024);
;   }
; DI void up_math(const u32x4 (&W)[16], const u32 (&pj)[16], float* __restrict__ yrow, int lane) {
;     ...
;   for (int j = 0; j < 16; ++j) {
;     const float h = __uint_as_float(pj[j] << 16);
;     const f2 hh = {h, h};
; #pragma unroll
;     for (int d = 0; d < 4; ++d) {
;       f2 lo = __builtin_amdgcn_cvt_pk_f32_fp8((int)W[j][d], false);
;       f2 hi = __builtin_amdgcn_cvt_pk_f32_fp8((int)W[j][d], true);
;       y[2 * d] = lo * hh + y[2 * d];
;       y[2 * d + 1] = hi * hh + y[2 * d + 1];
;     }
;   }
.LBB0_827:
	ds_read2_b32 v[210:211], v145 offset1:8
	ds_read2_b32 v[208:209], v145 offset0:16 offset1:24
	s_waitcnt lgkmcnt(1)
	v_lshlrev_b32_sdwa v132, v215, v210 dst_sel:DWORD dst_unused:UNUSED_PAD src0_sel:DWORD src1_sel:WORD_1
	v_add_u32_e32 v68, v250, v132
	v_lshlrev_b32_sdwa v132, v215, v211 dst_sel:DWORD dst_unused:UNUSED_PAD src0_sel:DWORD src1_sel:WORD_1
	v_add_u32_e32 v70, v250, v132
	s_waitcnt lgkmcnt(0)
	v_lshlrev_b32_sdwa v132, v215, v208 dst_sel:DWORD dst_unused:UNUSED_PAD src0_sel:DWORD src1_sel:WORD_1
	global_load_dwordx4 v[128:131], v68, s[98:99]
	global_load_dwordx4 v[124:127], v70, s[98:99]
	ds_read2_b32 v[206:207], v145 offset0:32 offset1:40
	v_add_u32_e32 v68, v250, v132
	v_lshlrev_b32_sdwa v132, v215, v209 dst_sel:DWORD dst_unused:UNUSED_PAD src0_sel:DWORD src1_sel:WORD_1
	v_add_u32_e32 v70, v250, v132
	global_load_dwordx4 v[120:123], v68, s[98:99]
	global_load_dwordx4 v[116:119], v70, s[98:99]
	ds_read2_b32 v[204:205], v145 offset0:48 offset1:56
	s_waitcnt lgkmcnt(1)
	v_lshlrev_b32_sdwa v132, v215, v206 dst_sel:DWORD dst_unused:UNUSED_PAD src0_sel:DWORD src1_sel:WORD_1
	v_add_u32_e32 v68, v250, v132
	v_lshlrev_b32_sdwa v132, v215, v207 dst_sel:DWORD dst_unused:UNUSED_PAD src0_sel:DWORD src1_sel:WORD_1
	v_add_u32_e32 v70, v250, v132
	global_load_dwordx4 v[112:115], v68, s[98:99]
	global_load_dwordx4 v[108:111], v70, s[98:99]
	s_waitcnt lgkmcnt(0)
	v_lshlrev_b32_sdwa v132, v215, v204 dst_sel:DWORD dst_unused:UNUSED_PAD src0_sel:DWORD src1_sel:WORD_1
	ds_read2_b32 v[202:203], v145 offset0:64 offset1:72
	v_add_u32_e32 v68, v250, v132
	v_lshlrev_b32_sdwa v132, v215, v205 dst_sel:DWORD dst_unused:UNUSED_PAD src0_sel:DWORD src1_sel:WORD_1
	v_add_u32_e32 v70, v250, v132
	global_load_dwordx4 v[104:107], v68, s[98:99]
	global_load_dwordx4 v[100:103], v70, s[98:99]
	ds_read2_b32 v[200:201], v145 offset0:80 offset1:88
	s_waitcnt lgkmcnt(1)
	v_lshlrev_b32_sdwa v132, v215, v202 dst_sel:DWORD dst_unused:UNUSED_PAD src0_sel:DWORD src1_sel:WORD_1
	v_add_u32_e32 v68, v250, v132
	v_lshlrev_b32_sdwa v132, v215, v203 dst_sel:DWORD dst_unused:UNUSED_PAD src0_sel:DWORD src1_sel:WORD_1
	v_add_u32_e32 v70, v250, v132
	global_load_dwordx4 v[96:99], v68, s[98:99]
	global_load_dwordx4 v[92:95], v70, s[98:99]
	s_waitcnt lgkmcnt(0)
	v_lshlrev_b32_sdwa v132, v215, v200 dst_sel:DWORD dst_unused:UNUSED_PAD src0_sel:DWORD src1_sel:WORD_1
	ds_read2_b32 v[198:199], v145 offset0:96 offset1:104
	v_add_u32_e32 v68, v250, v132
	v_lshlrev_b32_sdwa v132, v215, v201 dst_sel:DWORD dst_unused:UNUSED_PAD src0_sel:DWORD src1_sel:WORD_1
	v_add_u32_e32 v70, v250, v132
	global_load_dwordx4 v[88:91], v68, s[98:99]
	global_load_dwordx4 v[84:87], v70, s[98:99]
	ds_read2_b32 v[196:197], v145 offset0:112 offset1:120
	s_waitcnt lgkmcnt(1)
	v_lshlrev_b32_sdwa v132, v215, v198 dst_sel:DWORD dst_unused:UNUSED_PAD src0_sel:DWORD src1_sel:WORD_1
	v_add_u32_e32 v68, v250, v132
	v_lshlrev_b32_sdwa v132, v215, v199 dst_sel:DWORD dst_unused:UNUSED_PAD src0_sel:DWORD src1_sel:WORD_1
	v_add_u32_e32 v70, v250, v132
	s_waitcnt lgkmcnt(0)
	v_lshlrev_b32_sdwa v132, v215, v196 dst_sel:DWORD dst_unused:UNUSED_PAD src0_sel:DWORD src1_sel:WORD_1
	global_load_dwordx4 v[80:83], v68, s[98:99]
	global_load_dwordx4 v[76:79], v70, s[98:99]
	v_add_u32_e32 v68, v250, v132
	v_lshlrev_b32_sdwa v132, v215, v197 dst_sel:DWORD dst_unused:UNUSED_PAD src0_sel:DWORD src1_sel:WORD_1
	v_add_u32_e32 v70, v250, v132
	global_load_dwordx4 v[72:75], v68, s[98:99]
	s_nop 0
	global_load_dwordx4 v[68:71], v70, s[98:99]
	s_waitcnt vmcnt(31)
	v_cvt_pk_f32_fp8_e32 v[216:217], v4
	v_cvt_pk_f32_fp8_sdwa v[226:227], v4 src0_sel:WORD_1
	v_cvt_pk_f32_fp8_e32 v[228:229], v5
	v_cvt_pk_f32_fp8_sdwa v[230:231], v5 src0_sel:WORD_1
	v_cvt_pk_f32_fp8_e32 v[232:233], v6
	v_cvt_pk_f32_fp8_sdwa v[234:235], v6 src0_sel:WORD_1
	v_cvt_pk_f32_fp8_e32 v[236:237], v7
	v_cvt_pk_f32_fp8_sdwa v[238:239], v7 src0_sel:WORD_1
	s_waitcnt vmcnt(30)
	v_cvt_pk_f32_fp8_e32 v[240:241], v8
	v_cvt_pk_f32_fp8_sdwa v[242:243], v8 src0_sel:WORD_1
	v_cvt_pk_f32_fp8_e32 v[244:245], v9
	v_cvt_pk_f32_fp8_sdwa v[246:247], v9 src0_sel:WORD_1
	v_lshlrev_b32_e32 v132, 16, v178
	v_pk_fma_f32 v[216:217], v[132:133], v[216:217], 0 op_sel_hi:[0,1,0]
	v_pk_fma_f32 v[226:227], v[132:133], v[226:227], 0 op_sel_hi:[0,1,0]
	v_pk_fma_f32 v[228:229], v[132:133], v[228:229], 0 op_sel_hi:[0,1,0]
	v_pk_fma_f32 v[230:231], v[132:133], v[230:231], 0 op_sel_hi:[0,1,0]
	v_pk_fma_f32 v[232:233], v[132:133], v[232:233], 0 op_sel_hi:[0,1,0]
	v_pk_fma_f32 v[234:235], v[132:133], v[234:235], 0 op_sel_hi:[0,1,0]
	v_pk_fma_f32 v[236:237], v[132:133], v[236:237], 0 op_sel_hi:[0,1,0]
	v_pk_fma_f32 v[238:239], v[132:133], v[238:239], 0 op_sel_hi:[0,1,0]
	v_lshlrev_b32_e32 v132, 16, v179
	v_pk_fma_f32 v[216:217], v[132:133], v[240:241], v[216:217] op_sel_hi:[0,1,1]
	v_cvt_pk_f32_fp8_e32 v[240:241], v10
	v_pk_fma_f32 v[226:227], v[132:133], v[242:243], v[226:227] op_sel_hi:[0,1,1]
	v_pk_fma_f32 v[228:229], v[132:133], v[244:245], v[228:229] op_sel_hi:[0,1,1]
	v_pk_fma_f32 v[230:231], v[132:133], v[246:247], v[230:231] op_sel_hi:[0,1,1]
	v_cvt_pk_f32_fp8_sdwa v[242:243], v10 src0_sel:WORD_1
	v_cvt_pk_f32_fp8_e32 v[244:245], v11
	v_cvt_pk_f32_fp8_sdwa v[246:247], v11 src0_sel:WORD_1
	v_pk_fma_f32 v[232:233], v[132:133], v[240:241], v[232:233] op_sel_hi:[0,1,1]
	s_waitcnt vmcnt(29)
; DI void up_math(const u32x4 (&W)[16], const u32 (&pj)[16], float* __restrict__ yrow, int lane) {
;     ...
;   for (int j = 0; j < 16; ++j) {
;     const float h = __uint_as_float(pj[j] << 16);
;     const f2 hh = {h, h};
; #pragma unroll
;     for (int d = 0; d < 4; ++d) {
;       f2 lo = __builtin_amdgcn_cvt_pk_f32_fp8((int)W[j][d], false);
;       f2 hi = __builtin_amdgcn_cvt_pk_f32_fp8((int)W[j][d], true);
;       y[2 * d] = lo * hh + y[2 * d];
;       y[2 * d + 1] = hi * hh + y[2 * d + 1];
;     }
;   }
	v_cvt_pk_f32_fp8_e32 v[240:241], v12
	v_pk_fma_f32 v[234:235], v[132:133], v[242:243], v[234:235] op_sel_hi:[0,1,1]
	v_pk_fma_f32 v[236:237], v[132:133], v[244:245], v[236:237] op_sel_hi:[0,1,1]
	v_pk_fma_f32 v[238:239], v[132:133], v[246:247], v[238:239] op_sel_hi:[0,1,1]
	v_cvt_pk_f32_fp8_sdwa v[242:243], v12 src0_sel:WORD_1
	v_cvt_pk_f32_fp8_e32 v[244:245], v13
	v_cvt_pk_f32_fp8_sdwa v[246:247], v13 src0_sel:WORD_1
	v_lshlrev_b32_e32 v132, 16, v180
	v_pk_fma_f32 v[216:217], v[132:133], v[240:241], v[216:217] op_sel_hi:[0,1,1]
	v_cvt_pk_f32_fp8_e32 v[240:241], v14
	v_pk_fma_f32 v[226:227], v[132:133], v[242:243], v[226:227] op_sel_hi:[0,1,1]
	v_pk_fma_f32 v[228:229], v[132:133], v[244:245], v[228:229] op_sel_hi:[0,1,1]
	v_pk_fma_f32 v[230:231], v[132:133], v[246:247], v[230:231] op_sel_hi:[0,1,1]
	v_cvt_pk_f32_fp8_sdwa v[242:243], v14 src0_sel:WORD_1
	v_cvt_pk_f32_fp8_e32 v[244:245], v15
	v_cvt_pk_f32_fp8_sdwa v[246:247], v15 src0_sel:WORD_1
	v_pk_fma_f32 v[232:233], v[132:133], v[240:241], v[232:233] op_sel_hi:[0,1,1]
	s_waitcnt vmcnt(28)
	v_cvt_pk_f32_fp8_e32 v[240:241], v16
	v_pk_fma_f32 v[234:235], v[132:133], v[242:243], v[234:235] op_sel_hi:[0,1,1]
	v_pk_fma_f32 v[236:237], v[132:133], v[244:245], v[236:237] op_sel_hi:[0,1,1]
	v_pk_fma_f32 v[238:239], v[132:133], v[246:247], v[238:239] op_sel_hi:[0,1,1]
	v_cvt_pk_f32_fp8_sdwa v[242:243], v16 src0_sel:WORD_1
	v_cvt_pk_f32_fp8_e32 v[244:245], v17
	v_cvt_pk_f32_fp8_sdwa v[246:247], v17 src0_sel:WORD_1
	v_lshlrev_b32_e32 v132, 16, v181
	v_pk_fma_f32 v[216:217], v[132:133], v[240:241], v[216:217] op_sel_hi:[0,1,1]
	v_cvt_pk_f32_fp8_e32 v[240:241], v18
	v_pk_fma_f32 v[226:227], v[132:133], v[242:243], v[226:227] op_sel_hi:[0,1,1]
	v_pk_fma_f32 v[228:229], v[132:133], v[244:245], v[228:229] op_sel_hi:[0,1,1]
	v_pk_fma_f32 v[230:231], v[132:133], v[246:247], v[230:231] op_sel_hi:[0,1,1]
	v_cvt_pk_f32_fp8_sdwa v[242:243], v18 src0_sel:WORD_1
	v_cvt_pk_f32_fp8_e32 v[244:245], v19
	v_cvt_pk_f32_fp8_sdwa v[246:247], v19 src0_sel:WORD_1
	v_pk_fma_f32 v[232:233], v[132:133], v[240:241], v[232:233] op_sel_hi:[0,1,1]
	s_waitcnt vmcnt(27)
	v_cvt_pk_f32_fp8_e32 v[240:241], v20
	v_pk_fma_f32 v[234:235], v[132:133], v[242:243], v[234:235] op_sel_hi:[0,1,1]
	v_pk_fma_f32 v[236:237], v[132:133], v[244:245], v[236:237] op_sel_hi:[0,1,1]
	v_pk_fma_f32 v[238:239], v[132:133], v[246:247], v[238:239] op_sel_hi:[0,1,1]
	v_cvt_pk_f32_fp8_sdwa v[242:243], v20 src0_sel:WORD_1
	v_cvt_pk_f32_fp8_e32 v[244:245], v21
	v_cvt_pk_f32_fp8_sdwa v[246:247], v21 src0_sel:WORD_1
	v_lshlrev_b32_e32 v132, 16, v182
	v_pk_fma_f32 v[216:217], v[132:133], v[240:241], v[216:217] op_sel_hi:[0,1,1]
	v_cvt_pk_f32_fp8_e32 v[240:241], v22
	v_pk_fma_f32 v[226:227], v[132:133], v[242:243], v[226:227] op_sel_hi:[0,1,1]
	v_pk_fma_f32 v[228:229], v[132:133], v[244:245], v[228:229] op_sel_hi:[0,1,1]
	v_pk_fma_f32 v[230:231], v[132:133], v[246:247], v[230:231] op_sel_hi:[0,1,1]
	v_cvt_pk_f32_fp8_sdwa v[242:243], v22 src0_sel:WORD_1
	v_cvt_pk_f32_fp8_e32 v[244:245], v23
	v_cvt_pk_f32_fp8_sdwa v[246:247], v23 src0_sel:WORD_1
	v_pk_fma_f32 v[232:233], v[132:133], v[240:241], v[232:233] op_sel_hi:[0,1,1]
	s_waitcnt vmcnt(26)
	v_cvt_pk_f32_fp8_e32 v[240:241], v24
	v_pk_fma_f32 v[234:235], v[132:133], v[242:243], v[234:235] op_sel_hi:[0,1,1]
	v_pk_fma_f32 v[236:237], v[132:133], v[244:245], v[236:237] op_sel_hi:[0,1,1]
	v_pk_fma_f32 v[238:239], v[132:133], v[246:247], v[238:239] op_sel_hi:[0,1,1]
	v_cvt_pk_f32_fp8_sdwa v[242:243], v24 src0_sel:WORD_1
	v_cvt_pk_f32_fp8_e32 v[244:245], v25
	v_cvt_pk_f32_fp8_sdwa v[246:247], v25 src0_sel:WORD_1
	v_lshlrev_b32_e32 v132, 16, v183
	v_pk_fma_f32 v[216:217], v[132:133], v[240:241], v[216:217] op_sel_hi:[0,1,1]
	v_cvt_pk_f32_fp8_e32 v[240:241], v26
	v_pk_fma_f32 v[226:227], v[132:133], v[242:243], v[226:227] op_sel_hi:[0,1,1]
	v_pk_fma_f32 v[228:229], v[132:133], v[244:245], v[228:229] op_sel_hi:[0,1,1]
	v_pk_fma_f32 v[230:231], v[132:133], v[246:247], v[230:231] op_sel_hi:[0,1,1]
	v_cvt_pk_f32_fp8_sdwa v[242:243], v26 src0_sel:WORD_1
	v_cvt_pk_f32_fp8_e32 v[244:245], v27
	v_cvt_pk_f32_fp8_sdwa v[246:247], v27 src0_sel:WORD_1
	v_pk_fma_f32 v[232:233], v[132:133], v[240:241], v[232:233] op_sel_hi:[0,1,1]
	s_waitcnt vmcnt(25)
	v_cvt_pk_f32_fp8_e32 v[240:241], v28
	v_pk_fma_f32 v[234:235], v[132:133], v[242:243], v[234:235] op_sel_hi:[0,1,1]
	v_pk_fma_f32 v[236:237], v[132:133], v[244:245], v[236:237] op_sel_hi:[0,1,1]
	v_pk_fma_f32 v[238:239], v[132:133], v[246:247], v[238:239] op_sel_hi:[0,1,1]
	v_cvt_pk_f32_fp8_sdwa v[242:243], v28 src0_sel:WORD_1
	v_cvt_pk_f32_fp8_e32 v[244:245], v29
	v_cvt_pk_f32_fp8_sdwa v[246:247], v29 src0_sel:WORD_1
	v_lshlrev_b32_e32 v132, 16, v184
	v_pk_fma_f32 v[216:217], v[132:133], v[240:241], v[216:217] op_sel_hi:[0,1,1]
	v_cvt_pk_f32_fp8_e32 v[240:241], v30
	v_pk_fma_f32 v[226:227], v[132:133], v[242:243], v[226:227] op_sel_hi:[0,1,1]
	v_pk_fma_f32 v[228:229], v[132:133], v[244:245], v[228:229] op_sel_hi:[0,1,1]
	v_pk_fma_f32 v[230:231], v[132:133], v[246:247], v[230:231] op_sel_hi:[0,1,1]
	v_cvt_pk_f32_fp8_sdwa v[242:243], v30 src0_sel:WORD_1
	v_cvt_pk_f32_fp8_e32 v[244:245], v31
	v_cvt_pk_f32_fp8_sdwa v[246:247], v31 src0_sel:WORD_1
	v_pk_fma_f32 v[232:233], v[132:133], v[240:241], v[232:233] op_sel_hi:[0,1,1]
	s_waitcnt vmcnt(24)
; DI void up_math(const u32x4 (&W)[16], const u32 (&pj)[16], float* __restrict__ yrow, int lane) {
;     ...
;   for (int j = 0; j < 16; ++j) {
;     const float h = __uint_as_float(pj[j] << 16);
;     const f2 hh = {h, h};
; #pragma unroll
;     for (int d = 0; d < 4; ++d) {
;       f2 lo = __builtin_amdgcn_cvt_pk_f32_fp8((int)W[j][d], false);
;       f2 hi = __builtin_amdgcn_cvt_pk_f32_fp8((int)W[j][d], true);
;       y[2 * d] = lo * hh + y[2 * d];
;       y[2 * d + 1] = hi * hh + y[2 * d + 1];
;     }
;   }
	v_cvt_pk_f32_fp8_e32 v[240:241], v32
	v_pk_fma_f32 v[234:235], v[132:133], v[242:243], v[234:235] op_sel_hi:[0,1,1]
	v_pk_fma_f32 v[236:237], v[132:133], v[244:245], v[236:237] op_sel_hi:[0,1,1]
	v_pk_fma_f32 v[238:239], v[132:133], v[246:247], v[238:239] op_sel_hi:[0,1,1]
	v_cvt_pk_f32_fp8_sdwa v[242:243], v32 src0_sel:WORD_1
	v_cvt_pk_f32_fp8_e32 v[244:245], v33
	v_cvt_pk_f32_fp8_sdwa v[246:247], v33 src0_sel:WORD_1
	v_lshlrev_b32_e32 v132, 16, v185
	v_pk_fma_f32 v[216:217], v[132:133], v[240:241], v[216:217] op_sel_hi:[0,1,1]
	v_cvt_pk_f32_fp8_e32 v[240:241], v34
	v_pk_fma_f32 v[226:227], v[132:133], v[242:243], v[226:227] op_sel_hi:[0,1,1]
	v_pk_fma_f32 v[228:229], v[132:133], v[244:245], v[228:229] op_sel_hi:[0,1,1]
	v_pk_fma_f32 v[230:231], v[132:133], v[246:247], v[230:231] op_sel_hi:[0,1,1]
	v_cvt_pk_f32_fp8_sdwa v[242:243], v34 src0_sel:WORD_1
	v_cvt_pk_f32_fp8_e32 v[244:245], v35
	v_cvt_pk_f32_fp8_sdwa v[246:247], v35 src0_sel:WORD_1
	v_pk_fma_f32 v[232:233], v[132:133], v[240:241], v[232:233] op_sel_hi:[0,1,1]
	s_waitcnt vmcnt(23)
	v_cvt_pk_f32_fp8_e32 v[240:241], v36
	v_pk_fma_f32 v[234:235], v[132:133], v[242:243], v[234:235] op_sel_hi:[0,1,1]
	v_pk_fma_f32 v[236:237], v[132:133], v[244:245], v[236:237] op_sel_hi:[0,1,1]
	v_pk_fma_f32 v[238:239], v[132:133], v[246:247], v[238:239] op_sel_hi:[0,1,1]
	v_cvt_pk_f32_fp8_sdwa v[242:243], v36 src0_sel:WORD_1
	v_cvt_pk_f32_fp8_e32 v[244:245], v37
	v_cvt_pk_f32_fp8_sdwa v[246:247], v37 src0_sel:WORD_1
	v_lshlrev_b32_e32 v132, 16, v186
	v_pk_fma_f32 v[216:217], v[132:133], v[240:241], v[216:217] op_sel_hi:[0,1,1]
	v_cvt_pk_f32_fp8_e32 v[240:241], v38
	v_pk_fma_f32 v[226:227], v[132:133], v[242:243], v[226:227] op_sel_hi:[0,1,1]
	v_pk_fma_f32 v[228:229], v[132:133], v[244:245], v[228:229] op_sel_hi:[0,1,1]
	v_pk_fma_f32 v[230:231], v[132:133], v[246:247], v[230:231] op_sel_hi:[0,1,1]
	v_cvt_pk_f32_fp8_sdwa v[242:243], v38 src0_sel:WORD_1
	v_cvt_pk_f32_fp8_e32 v[244:245], v39
	v_cvt_pk_f32_fp8_sdwa v[246:247], v39 src0_sel:WORD_1
	v_pk_fma_f32 v[232:233], v[132:133], v[240:241], v[232:233] op_sel_hi:[0,1,1]
	s_waitcnt vmcnt(22)
	v_cvt_pk_f32_fp8_e32 v[240:241], v40
	v_pk_fma_f32 v[234:235], v[132:133], v[242:243], v[234:235] op_sel_hi:[0,1,1]
	v_pk_fma_f32 v[236:237], v[132:133], v[244:245], v[236:237] op_sel_hi:[0,1,1]
	v_pk_fma_f32 v[238:239], v[132:133], v[246:247], v[238:239] op_sel_hi:[0,1,1]
	v_cvt_pk_f32_fp8_sdwa v[242:243], v40 src0_sel:WORD_1
	v_cvt_pk_f32_fp8_e32 v[244:245], v41
	v_cvt_pk_f32_fp8_sdwa v[246:247], v41 src0_sel:WORD_1
	v_lshlrev_b32_e32 v132, 16, v187
	v_pk_fma_f32 v[216:217], v[132:133], v[240:241], v[216:217] op_sel_hi:[0,1,1]
	v_cvt_pk_f32_fp8_e32 v[240:241], v42
	v_pk_fma_f32 v[226:227], v[132:133], v[242:243], v[226:227] op_sel_hi:[0,1,1]
	v_pk_fma_f32 v[228:229], v[132:133], v[244:245], v[228:229] op_sel_hi:[0,1,1]
	v_pk_fma_f32 v[230:231], v[132:133], v[246:247], v[230:231] op_sel_hi:[0,1,1]
	v_cvt_pk_f32_fp8_sdwa v[242:243], v42 src0_sel:WORD_1
	v_cvt_pk_f32_fp8_e32 v[244:245], v43
	v_cvt_pk_f32_fp8_sdwa v[246:247], v43 src0_sel:WORD_1
	v_pk_fma_f32 v[232:233], v[132:133], v[240:241], v[232:233] op_sel_hi:[0,1,1]
	s_waitcnt vmcnt(21)
	v_cvt_pk_f32_fp8_e32 v[240:241], v44
	v_pk_fma_f32 v[234:235], v[132:133], v[242:243], v[234:235] op_sel_hi:[0,1,1]
	v_pk_fma_f32 v[236:237], v[132:133], v[244:245], v[236:237] op_sel_hi:[0,1,1]
	v_pk_fma_f32 v[238:239], v[132:133], v[246:247], v[238:239] op_sel_hi:[0,1,1]
	v_cvt_pk_f32_fp8_sdwa v[242:243], v44 src0_sel:WORD_1
	v_cvt_pk_f32_fp8_e32 v[244:245], v45
	v_cvt_pk_f32_fp8_sdwa v[246:247], v45 src0_sel:WORD_1
	v_lshlrev_b32_e32 v132, 16, v190
	v_pk_fma_f32 v[216:217], v[132:133], v[240:241], v[216:217] op_sel_hi:[0,1,1]
	v_cvt_pk_f32_fp8_e32 v[240:241], v46
	v_pk_fma_f32 v[226:227], v[132:133], v[242:243], v[226:227] op_sel_hi:[0,1,1]
	v_pk_fma_f32 v[228:229], v[132:133], v[244:245], v[228:229] op_sel_hi:[0,1,1]
	v_pk_fma_f32 v[230:231], v[132:133], v[246:247], v[230:231] op_sel_hi:[0,1,1]
	v_cvt_pk_f32_fp8_sdwa v[242:243], v46 src0_sel:WORD_1
	v_cvt_pk_f32_fp8_e32 v[244:245], v47
	v_cvt_pk_f32_fp8_sdwa v[246:247], v47 src0_sel:WORD_1
	v_pk_fma_f32 v[232:233], v[132:133], v[240:241], v[232:233] op_sel_hi:[0,1,1]
	s_waitcnt vmcnt(20)
	v_cvt_pk_f32_fp8_e32 v[240:241], v48
	v_pk_fma_f32 v[234:235], v[132:133], v[242:243], v[234:235] op_sel_hi:[0,1,1]
	v_pk_fma_f32 v[236:237], v[132:133], v[244:245], v[236:237] op_sel_hi:[0,1,1]
	v_pk_fma_f32 v[238:239], v[132:133], v[246:247], v[238:239] op_sel_hi:[0,1,1]
	v_cvt_pk_f32_fp8_sdwa v[242:243], v48 src0_sel:WORD_1
	v_cvt_pk_f32_fp8_e32 v[244:245], v49
	v_cvt_pk_f32_fp8_sdwa v[246:247], v49 src0_sel:WORD_1
	v_lshlrev_b32_e32 v132, 16, v191
	v_pk_fma_f32 v[216:217], v[132:133], v[240:241], v[216:217] op_sel_hi:[0,1,1]
	v_cvt_pk_f32_fp8_e32 v[240:241], v50
	v_pk_fma_f32 v[226:227], v[132:133], v[242:243], v[226:227] op_sel_hi:[0,1,1]
	v_pk_fma_f32 v[228:229], v[132:133], v[244:245], v[228:229] op_sel_hi:[0,1,1]
	v_pk_fma_f32 v[230:231], v[132:133], v[246:247], v[230:231] op_sel_hi:[0,1,1]
	v_cvt_pk_f32_fp8_sdwa v[242:243], v50 src0_sel:WORD_1
	v_cvt_pk_f32_fp8_e32 v[244:245], v51
	v_cvt_pk_f32_fp8_sdwa v[246:247], v51 src0_sel:WORD_1
	v_pk_fma_f32 v[232:233], v[132:133], v[240:241], v[232:233] op_sel_hi:[0,1,1]
	s_waitcnt vmcnt(19)
; DI void up_math(const u32x4 (&W)[16], const u32 (&pj)[16], float* __restrict__ yrow, int lane) {
;     ...
;   for (int j = 0; j < 16; ++j) {
;     const float h = __uint_as_float(pj[j] << 16);
;     const f2 hh = {h, h};
; #pragma unroll
;     for (int d = 0; d < 4; ++d) {
;       f2 lo = __builtin_amdgcn_cvt_pk_f32_fp8((int)W[j][d], false);
;       f2 hi = __builtin_amdgcn_cvt_pk_f32_fp8((int)W[j][d], true);
;       y[2 * d] = lo * hh + y[2 * d];
;       y[2 * d + 1] = hi * hh + y[2 * d + 1];
;     }
;   }
;   const bool b5 = lane & 32, b4 = lane & 16, b3 = lane & 8;
;   f2 q4[4];
; #pragma unroll
;   for (int i = 0; i < 4; ++i) {
;     f2 snd = b5 ? y[i] : y[i + 4]; f2 kp = b5 ? y[i + 4] : y[i];
;     q4[i] = f2{kp.x + __shfl_xor(snd.x, 32), kp.y + __shfl_xor(snd.y, 32)};
;   }
;   f2 r2[2];
; #pragma unroll
;   for (int i = 0; i < 2; ++i) {
;     f2 snd = b4 ? q4[i] : q4[i + 2]; f2 kp = b4 ? q4[i + 2] : q4[i];
;     r2[i] = f2{kp.x + __shfl_xor(snd.x, 16), kp.y + __shfl_xor(snd.y, 16)};
;   }
;   f2 a;
;   { f2 snd = b3 ? r2[0] : r2[1]; f2 kp = b3 ? r2[1] : r2[0]; a = f2{kp.x + __shfl_xor(snd.x, 8), kp.y + __shfl_xor(snd.y, 8)}; }
;   const int ci = (b5 ? 4 : 0) + (b4 ? 2 : 0) + (b3 ? 1 : 0);
;   *(float2*)(yrow + (lane & 7) * 16 + 2 * ci) = make_float2(a.x, a.y);
	v_cvt_pk_f32_fp8_e32 v[240:241], v52
	v_pk_fma_f32 v[234:235], v[132:133], v[242:243], v[234:235] op_sel_hi:[0,1,1]
	v_pk_fma_f32 v[236:237], v[132:133], v[244:245], v[236:237] op_sel_hi:[0,1,1]
	v_pk_fma_f32 v[238:239], v[132:133], v[246:247], v[238:239] op_sel_hi:[0,1,1]
	v_cvt_pk_f32_fp8_sdwa v[242:243], v52 src0_sel:WORD_1
	v_cvt_pk_f32_fp8_e32 v[244:245], v53
	v_cvt_pk_f32_fp8_sdwa v[246:247], v53 src0_sel:WORD_1
	v_lshlrev_b32_e32 v132, 16, v192
	v_pk_fma_f32 v[216:217], v[132:133], v[240:241], v[216:217] op_sel_hi:[0,1,1]
	v_cvt_pk_f32_fp8_e32 v[240:241], v54
	v_pk_fma_f32 v[226:227], v[132:133], v[242:243], v[226:227] op_sel_hi:[0,1,1]
	v_pk_fma_f32 v[228:229], v[132:133], v[244:245], v[228:229] op_sel_hi:[0,1,1]
	v_pk_fma_f32 v[230:231], v[132:133], v[246:247], v[230:231] op_sel_hi:[0,1,1]
	v_cvt_pk_f32_fp8_sdwa v[242:243], v54 src0_sel:WORD_1
	v_cvt_pk_f32_fp8_e32 v[244:245], v55
	v_cvt_pk_f32_fp8_sdwa v[246:247], v55 src0_sel:WORD_1
	v_pk_fma_f32 v[232:233], v[132:133], v[240:241], v[232:233] op_sel_hi:[0,1,1]
	s_waitcnt vmcnt(18)
	v_cvt_pk_f32_fp8_e32 v[240:241], v56
	v_pk_fma_f32 v[234:235], v[132:133], v[242:243], v[234:235] op_sel_hi:[0,1,1]
	v_pk_fma_f32 v[236:237], v[132:133], v[244:245], v[236:237] op_sel_hi:[0,1,1]
	v_pk_fma_f32 v[238:239], v[132:133], v[246:247], v[238:239] op_sel_hi:[0,1,1]
	v_cvt_pk_f32_fp8_sdwa v[242:243], v56 src0_sel:WORD_1
	v_cvt_pk_f32_fp8_e32 v[244:245], v57
	v_cvt_pk_f32_fp8_sdwa v[246:247], v57 src0_sel:WORD_1
	v_lshlrev_b32_e32 v132, 16, v193
	v_pk_fma_f32 v[216:217], v[132:133], v[240:241], v[216:217] op_sel_hi:[0,1,1]
	v_cvt_pk_f32_fp8_e32 v[240:241], v58
	v_pk_fma_f32 v[226:227], v[132:133], v[242:243], v[226:227] op_sel_hi:[0,1,1]
	v_pk_fma_f32 v[228:229], v[132:133], v[244:245], v[228:229] op_sel_hi:[0,1,1]
	v_pk_fma_f32 v[230:231], v[132:133], v[246:247], v[230:231] op_sel_hi:[0,1,1]
	v_cvt_pk_f32_fp8_sdwa v[242:243], v58 src0_sel:WORD_1
	v_cvt_pk_f32_fp8_e32 v[244:245], v59
	v_cvt_pk_f32_fp8_sdwa v[246:247], v59 src0_sel:WORD_1
	v_pk_fma_f32 v[232:233], v[132:133], v[240:241], v[232:233] op_sel_hi:[0,1,1]
	s_waitcnt vmcnt(17)
	v_cvt_pk_f32_fp8_e32 v[240:241], v60
	v_pk_fma_f32 v[234:235], v[132:133], v[242:243], v[234:235] op_sel_hi:[0,1,1]
	v_pk_fma_f32 v[236:237], v[132:133], v[244:245], v[236:237] op_sel_hi:[0,1,1]
	v_pk_fma_f32 v[238:239], v[132:133], v[246:247], v[238:239] op_sel_hi:[0,1,1]
	v_cvt_pk_f32_fp8_sdwa v[242:243], v60 src0_sel:WORD_1
	v_cvt_pk_f32_fp8_e32 v[244:245], v61
	v_cvt_pk_f32_fp8_sdwa v[246:247], v61 src0_sel:WORD_1
	v_lshlrev_b32_e32 v132, 16, v194
	v_pk_fma_f32 v[216:217], v[132:133], v[240:241], v[216:217] op_sel_hi:[0,1,1]
	v_cvt_pk_f32_fp8_e32 v[240:241], v62
	v_pk_fma_f32 v[226:227], v[132:133], v[242:243], v[226:227] op_sel_hi:[0,1,1]
	v_pk_fma_f32 v[228:229], v[132:133], v[244:245], v[228:229] op_sel_hi:[0,1,1]
	v_pk_fma_f32 v[230:231], v[132:133], v[246:247], v[230:231] op_sel_hi:[0,1,1]
	v_cvt_pk_f32_fp8_sdwa v[242:243], v62 src0_sel:WORD_1
	v_cvt_pk_f32_fp8_e32 v[244:245], v63
	v_cvt_pk_f32_fp8_sdwa v[246:247], v63 src0_sel:WORD_1
	v_pk_fma_f32 v[232:233], v[132:133], v[240:241], v[232:233] op_sel_hi:[0,1,1]
	s_waitcnt vmcnt(16)
	v_cvt_pk_f32_fp8_e32 v[240:241], v64
	v_pk_fma_f32 v[234:235], v[132:133], v[242:243], v[234:235] op_sel_hi:[0,1,1]
	v_pk_fma_f32 v[236:237], v[132:133], v[244:245], v[236:237] op_sel_hi:[0,1,1]
	v_pk_fma_f32 v[238:239], v[132:133], v[246:247], v[238:239] op_sel_hi:[0,1,1]
	v_cvt_pk_f32_fp8_sdwa v[242:243], v64 src0_sel:WORD_1
	v_cvt_pk_f32_fp8_e32 v[244:245], v65
	v_cvt_pk_f32_fp8_sdwa v[246:247], v65 src0_sel:WORD_1
	v_lshlrev_b32_e32 v132, 16, v195
	v_pk_fma_f32 v[216:217], v[132:133], v[240:241], v[216:217] op_sel_hi:[0,1,1]
	v_cvt_pk_f32_fp8_e32 v[240:241], v66
	v_pk_fma_f32 v[226:227], v[132:133], v[242:243], v[226:227] op_sel_hi:[0,1,1]
	v_pk_fma_f32 v[228:229], v[132:133], v[244:245], v[228:229] op_sel_hi:[0,1,1]
	v_pk_fma_f32 v[230:231], v[132:133], v[246:247], v[230:231] op_sel_hi:[0,1,1]
	v_cvt_pk_f32_fp8_sdwa v[242:243], v66 src0_sel:WORD_1
	v_cvt_pk_f32_fp8_e32 v[244:245], v67
	v_cvt_pk_f32_fp8_sdwa v[246:247], v67 src0_sel:WORD_1
	v_pk_fma_f32 v[232:233], v[132:133], v[240:241], v[232:233] op_sel_hi:[0,1,1]
	v_pk_fma_f32 v[234:235], v[132:133], v[242:243], v[234:235] op_sel_hi:[0,1,1]
	v_pk_fma_f32 v[236:237], v[132:133], v[244:245], v[236:237] op_sel_hi:[0,1,1]
	v_pk_fma_f32 v[238:239], v[132:133], v[246:247], v[238:239] op_sel_hi:[0,1,1]
	s_nop 1
	v_permlane32_swap_b32_e32 v216, v232
	v_permlane32_swap_b32_e32 v217, v233
	v_permlane32_swap_b32_e32 v228, v236
	v_permlane32_swap_b32_e32 v229, v237
	v_permlane32_swap_b32_e32 v226, v234
	v_permlane32_swap_b32_e32 v227, v235
	v_permlane32_swap_b32_e32 v230, v238
	v_permlane32_swap_b32_e32 v231, v239
	v_pk_add_f32 v[216:217], v[216:217], v[232:233]
	v_pk_add_f32 v[228:229], v[228:229], v[236:237]
	v_pk_add_f32 v[226:227], v[226:227], v[234:235]
	v_pk_add_f32 v[230:231], v[230:231], v[238:239]
	s_nop 1
	v_permlane16_swap_b32_e32 v216, v228
	v_permlane16_swap_b32_e32 v217, v229
	v_permlane16_swap_b32_e32 v226, v230
	v_permlane16_swap_b32_e32 v227, v231
	v_pk_add_f32 v[216:217], v[216:217], v[228:229]
	v_pk_add_f32 v[226:227], v[226:227], v[230:231]
	s_nop 0
	v_cndmask_b32_e64 v132, v217, v227, s[14:15]
	v_cndmask_b32_e64 v147, v216, v226, s[14:15]
	ds_bpermute_b32 v228, v143, v147
	ds_bpermute_b32 v229, v143, v132
	v_cndmask_b32_e64 v217, v227, v217, s[14:15]
	v_cndmask_b32_e64 v216, v226, v216, s[14:15]
	s_waitcnt lgkmcnt(0)
	v_pk_add_f32 v[216:217], v[216:217], v[228:229]
	global_store_dwordx2 v[188:189], v[216:217], off
	s_cmp_gt_u32 s44, 13
	s_cselect_b64 s[28:29], -1, 0
	s_and_b64 vcc, exec, s[28:29]
	s_cbranch_vccnz .LBB0_826
; DI void up_issue(u32x4 (&W)[16], u32 (&pj)[16], const u32* pl, const unsigned char* wbase, int grp) {
; #pragma unroll
;   for (int j = 0; j < 16; ++j) {
;     pj[j] = pl[8 * j + grp];
;     W[j] = *(const u32x4*)(wbase + (size_t)(pj[j] >> 16) * 1024);
;   }
; }
	ds_read2_b32 v[178:179], v145 offset0:128 offset1:136
	ds_read2_b32 v[180:181], v145 offset0:144 offset1:152
	s_waitcnt lgkmcnt(1)
	v_lshlrev_b32_sdwa v132, v215, v178 dst_sel:DWORD dst_unused:UNUSED_PAD src0_sel:DWORD src1_sel:WORD_1
	v_add_u32_e32 v4, v250, v132
	v_lshlrev_b32_sdwa v132, v215, v179 dst_sel:DWORD dst_unused:UNUSED_PAD src0_sel:DWORD src1_sel:WORD_1
	v_add_u32_e32 v8, v250, v132
	s_waitcnt lgkmcnt(0)
	v_lshlrev_b32_sdwa v132, v215, v180 dst_sel:DWORD dst_unused:UNUSED_PAD src0_sel:DWORD src1_sel:WORD_1
	global_load_dwordx4 v[4:7], v4, s[98:99]
	s_nop 0
	global_load_dwordx4 v[8:11], v8, s[98:99]
	v_add_u32_e32 v12, v250, v132
	ds_read2_b32 v[182:183], v145 offset0:160 offset1:168
	v_lshlrev_b32_sdwa v132, v215, v181 dst_sel:DWORD dst_unused:UNUSED_PAD src0_sel:DWORD src1_sel:WORD_1
	v_add_u32_e32 v16, v250, v132
	global_load_dwordx4 v[12:15], v12, s[98:99]
	s_nop 0
	global_load_dwordx4 v[16:19], v16, s[98:99]
	ds_read2_b32 v[184:185], v145 offset0:176 offset1:184
	s_waitcnt lgkmcnt(1)
	v_lshlrev_b32_sdwa v132, v215, v182 dst_sel:DWORD dst_unused:UNUSED_PAD src0_sel:DWORD src1_sel:WORD_1
	v_add_u32_e32 v20, v250, v132
	v_lshlrev_b32_sdwa v132, v215, v183 dst_sel:DWORD dst_unused:UNUSED_PAD src0_sel:DWORD src1_sel:WORD_1
	v_add_u32_e32 v24, v250, v132
	s_waitcnt lgkmcnt(0)
	v_lshlrev_b32_sdwa v132, v215, v184 dst_sel:DWORD dst_unused:UNUSED_PAD src0_sel:DWORD src1_sel:WORD_1
	global_load_dwordx4 v[20:23], v20, s[98:99]
	s_nop 0
	global_load_dwordx4 v[24:27], v24, s[98:99]
	v_add_u32_e32 v28, v250, v132
	ds_read2_b32 v[186:187], v145 offset0:192 offset1:200
	v_lshlrev_b32_sdwa v132, v215, v185 dst_sel:DWORD dst_unused:UNUSED_PAD src0_sel:DWORD src1_sel:WORD_1
	v_add_u32_e32 v32, v250, v132
	global_load_dwordx4 v[28:31], v28, s[98:99]
	s_nop 0
	global_load_dwordx4 v[32:35], v32, s[98:99]
	ds_read2_b32 v[190:191], v145 offset0:208 offset1:216
	s_waitcnt lgkmcnt(1)
	v_lshlrev_b32_sdwa v132, v215, v186 dst_sel:DWORD dst_unused:UNUSED_PAD src0_sel:DWORD src1_sel:WORD_1
	v_add_u32_e32 v36, v250, v132
	v_lshlrev_b32_sdwa v132, v215, v187 dst_sel:DWORD dst_unused:UNUSED_PAD src0_sel:DWORD src1_sel:WORD_1
	v_add_u32_e32 v40, v250, v132
	s_waitcnt lgkmcnt(0)
	v_lshlrev_b32_sdwa v132, v215, v190 dst_sel:DWORD dst_unused:UNUSED_PAD src0_sel:DWORD src1_sel:WORD_1
	global_load_dwordx4 v[36:39], v36, s[98:99]
	s_nop 0
	global_load_dwordx4 v[40:43], v40, s[98:99]
	v_add_u32_e32 v44, v250, v132
	ds_read2_b32 v[192:193], v145 offset0:224 offset1:232
	v_lshlrev_b32_sdwa v132, v215, v191 dst_sel:DWORD dst_unused:UNUSED_PAD src0_sel:DWORD src1_sel:WORD_1
	v_add_u32_e32 v48, v250, v132
	global_load_dwordx4 v[44:47], v44, s[98:99]
	s_nop 0
	global_load_dwordx4 v[48:51], v48, s[98:99]
	ds_read2_b32 v[194:195], v145 offset0:240 offset1:248
	s_waitcnt lgkmcnt(1)
	v_lshlrev_b32_sdwa v132, v215, v192 dst_sel:DWORD dst_unused:UNUSED_PAD src0_sel:DWORD src1_sel:WORD_1
	v_add_u32_e32 v52, v250, v132
	v_lshlrev_b32_sdwa v132, v215, v193 dst_sel:DWORD dst_unused:UNUSED_PAD src0_sel:DWORD src1_sel:WORD_1
	v_add_u32_e32 v56, v250, v132
	s_waitcnt lgkmcnt(0)
	v_lshlrev_b32_sdwa v132, v215, v194 dst_sel:DWORD dst_unused:UNUSED_PAD src0_sel:DWORD src1_sel:WORD_1
	v_add_u32_e32 v60, v250, v132
	v_lshlrev_b32_sdwa v132, v215, v195 dst_sel:DWORD dst_unused:UNUSED_PAD src0_sel:DWORD src1_sel:WORD_1
	v_add_u32_e32 v64, v250, v132
	global_load_dwordx4 v[52:55], v52, s[98:99]
	s_nop 0
	global_load_dwordx4 v[56:59], v56, s[98:99]
	s_nop 0
	global_load_dwordx4 v[60:63], v60, s[98:99]
	s_nop 0
	global_load_dwordx4 v[64:67], v64, s[98:99]
	s_branch .LBB0_826

; DI void peer_up_phase(const Params& p, unsigned char* smem, int layer, u32* ctr) {
;     ...
;   for (int si = 0; si < (stat ? 1 : 8); ++si) {
;     const int slice = stat ? xi : ((xcc + si) & 7);
;     for (;;) {
;       int item;
;       if (stat) { item = it_next; it_next += it_step; }
;       else {
;         __syncthreads();
;         if (tid == 0) *slot = (int)atomicAdd(ctr + slice, 1u);
;         __syncthreads();
;         item = *slot;
;       }
;       if (item >= 256) break;
;       const int t0 = item * 64 + 16 * w;
;       const unsigned char* wbase = wu + slice * 128 + c * 16;
.LBB0_1636:
	s_add_i32 s0, s30, s4
	s_and_b32 s0, s0, 7
	v_mov_b32_e32 v4, s0
	v_cndmask_b32_e64 v4, v2, v4, s[6:7]
	s_lshl_b32 s0, s0, 2
	v_lshlrev_b32_e32 v4, 7, v4
	s_add_u32 s20, s5, s0
	v_ashrrev_i32_e32 v5, 31, v4
	s_addc_u32 s21, s25, 0
	v_lshl_add_u64 v[174:175], v[134:135], 0, v[4:5]
	s_nop 0
	v_readfirstlane_b32 s98, v174
	v_readfirstlane_b32 s99, v175
	v_and_b32_e32 v250, 7, v160
	v_lshlrev_b32_e32 v250, 4, v250
	v_lshl_add_u64 v[176:177], v[4:5], 2, v[136:137]
	v_mov_b32_e32 v4, v0
	s_branch .LBB0_1639

; DI void up_issue(u32x4 (&W)[16], u32 (&pj)[16], const u32* pl, const unsigned char* wbase, int grp) {
; #pragma unroll
;   for (int j = 0; j < 16; ++j) {
;     pj[j] = pl[8 * j + grp];
;     W[j] = *(const u32x4*)(wbase + (size_t)(pj[j] >> 16) * 1024);
;   }
; }
; DI void peer_up_phase(const Params& p, unsigned char* smem, int layer, u32* ctr) {
;     ...
;       if (item >= 256) break;
;       const int t0 = item * 64 + 16 * w;
;       const unsigned char* wbase = wu + slice * 128 + c * 16;
;       {
;         const u32* src = hgp + (size_t)t0 * 128;
; #pragma unroll
;         for (int i = 0; i < 32; ++i) pl[i * 64 + lane] = src[i * 64 + lane];
;       }
;       float* ybase = yb + (size_t)t0 * 1024 + slice * 128;
;       u32x4 WA[16], WB[16];
;       u32 pA[16], pB[16];
;       up_issue(WA, pA, pl, wbase, grp);
.LBB0_1647:
	v_cmp_lt_i32_e32 vcc, s31, v4
	s_mov_b64 s[28:29], -1
	s_cbranch_vccnz .LBB0_1638
	s_waitcnt vmcnt(3)
	v_lshl_add_u32 v68, v4, 6, v3
	v_ashrrev_i32_e32 v69, 31, v68
	v_lshlrev_b64 v[4:5], 9, v[68:69]
	v_lshl_add_u64 v[4:5], s[16:17], 0, v[4:5]
	v_mov_b32_e32 v139, v133
	v_lshl_add_u64 v[6:7], v[4:5], 0, v[138:139]
	global_load_dword v38, v[6:7], off
	global_load_dword v39, v[6:7], off offset:256
	v_mov_b32_e32 v141, v133
	v_mov_b32_e32 v143, v133
	v_mov_b32_e32 v145, v133
	v_mov_b32_e32 v147, v133
	v_mov_b32_e32 v149, v133
	v_mov_b32_e32 v151, v133
	v_mov_b32_e32 v153, v133
	v_mov_b32_e32 v155, v133
	v_mov_b32_e32 v157, v133
	v_mov_b32_e32 v159, v133
	v_mov_b32_e32 v163, v133
	v_mov_b32_e32 v165, v133
	v_mov_b32_e32 v167, v133
	v_mov_b32_e32 v169, v133
	v_mov_b32_e32 v171, v133
	v_mov_b32_e32 v173, v133
	v_lshl_add_u64 v[8:9], v[4:5], 0, v[140:141]
	v_lshl_add_u64 v[10:11], v[4:5], 0, v[142:143]
	v_lshl_add_u64 v[12:13], v[4:5], 0, v[144:145]
	v_lshl_add_u64 v[14:15], v[4:5], 0, v[146:147]
	v_lshl_add_u64 v[16:17], v[4:5], 0, v[148:149]
	v_lshl_add_u64 v[18:19], v[4:5], 0, v[150:151]
	v_lshl_add_u64 v[20:21], v[4:5], 0, v[152:153]
	v_lshl_add_u64 v[22:23], v[4:5], 0, v[154:155]
	v_lshl_add_u64 v[24:25], v[4:5], 0, v[156:157]
	v_lshl_add_u64 v[26:27], v[4:5], 0, v[158:159]
	v_lshl_add_u64 v[28:29], v[4:5], 0, v[162:163]
	v_lshl_add_u64 v[30:31], v[4:5], 0, v[164:165]
	v_lshl_add_u64 v[32:33], v[4:5], 0, v[166:167]
	v_lshl_add_u64 v[34:35], v[4:5], 0, v[168:169]
	v_lshl_add_u64 v[36:37], v[4:5], 0, v[170:171]
	v_lshl_add_u64 v[4:5], v[4:5], 0, v[172:173]
	global_load_dword v70, v[6:7], off offset:512
	global_load_dword v71, v[6:7], off offset:768
	global_load_dword v72, v[6:7], off offset:1024
	global_load_dword v73, v[6:7], off offset:1280
	global_load_dword v74, v[6:7], off offset:1536
	global_load_dword v75, v[6:7], off offset:1792
	global_load_dword v76, v[6:7], off offset:2048
	global_load_dword v77, v[6:7], off offset:2304
	global_load_dword v78, v[6:7], off offset:2560
	global_load_dword v79, v[6:7], off offset:2816
	global_load_dword v80, v[6:7], off offset:3072
	global_load_dword v81, v[6:7], off offset:3328
	global_load_dword v82, v[6:7], off offset:3584
	global_load_dword v83, v[6:7], off offset:3840
	global_load_dword v84, v[8:9], off
	global_load_dword v85, v[10:11], off
	global_load_dword v86, v[12:13], off
	global_load_dword v87, v[14:15], off
	global_load_dword v88, v[16:17], off
	global_load_dword v89, v[18:19], off
	global_load_dword v90, v[20:21], off
	global_load_dword v91, v[22:23], off
	global_load_dword v92, v[24:25], off
	global_load_dword v93, v[26:27], off
	global_load_dword v94, v[28:29], off
	global_load_dword v95, v[30:31], off
	global_load_dword v96, v[32:33], off
	global_load_dword v97, v[34:35], off
	global_load_dword v98, v[36:37], off
	global_load_dword v99, v[4:5], off
	v_cmp_lt_i32_e32 vcc, v223, v218
	v_lshlrev_b64 v[68:69], 12, v[68:69]
	s_mov_b32 s36, 0
	v_lshl_add_u64 v[188:189], v[176:177], 0, v[68:69]
	v_mov_b32_e32 v145, v214
	s_waitcnt vmcnt(30)
	ds_write2st64_b32 v213, v38, v39 offset0:1 offset1:2
	ds_read2_b32 v[178:179], v212 offset0:64 offset1:72
	ds_read2_b32 v[180:181], v212 offset0:80 offset1:88
	ds_read2_b32 v[182:183], v212 offset0:96 offset1:104
	ds_read2_b32 v[184:185], v212 offset0:112 offset1:120
	ds_read2_b32 v[186:187], v212 offset0:128 offset1:136
	s_waitcnt lgkmcnt(4)
	v_lshlrev_b32_sdwa v132, v215, v178 dst_sel:DWORD dst_unused:UNUSED_PAD src0_sel:DWORD src1_sel:WORD_1
	v_add_u32_e32 v12, v250, v132
	v_lshlrev_b32_sdwa v132, v215, v179 dst_sel:DWORD dst_unused:UNUSED_PAD src0_sel:DWORD src1_sel:WORD_1
	v_add_u32_e32 v14, v250, v132
	s_waitcnt lgkmcnt(3)
	v_lshlrev_b32_sdwa v132, v215, v180 dst_sel:DWORD dst_unused:UNUSED_PAD src0_sel:DWORD src1_sel:WORD_1
	v_add_u32_e32 v20, v250, v132
	v_lshlrev_b32_sdwa v132, v215, v181 dst_sel:DWORD dst_unused:UNUSED_PAD src0_sel:DWORD src1_sel:WORD_1
	v_add_u32_e32 v22, v250, v132
	s_waitcnt lgkmcnt(2)
; DI void up_issue(u32x4 (&W)[16], u32 (&pj)[16], const u32* pl, const unsigned char* wbase, int grp) {
; #pragma unroll
;   for (int j = 0; j < 16; ++j) {
;     pj[j] = pl[8 * j + grp];
;     W[j] = *(const u32x4*)(wbase + (size_t)(pj[j] >> 16) * 1024);
;   }
; }
; DI void peer_up_phase(const Params& p, unsigned char* smem, int layer, u32* ctr) {
;     ...
;       {
;         const u32* src = hgp + (size_t)t0 * 128;
; #pragma unroll
;         for (int i = 0; i < 32; ++i) pl[i * 64 + lane] = src[i * 64 + lane];
;       }
;       float* ybase = yb + (size_t)t0 * 1024 + slice * 128;
;       u32x4 WA[16], WB[16];
;       u32 pA[16], pB[16];
;       up_issue(WA, pA, pl, wbase, grp);
	v_lshlrev_b32_sdwa v132, v215, v182 dst_sel:DWORD dst_unused:UNUSED_PAD src0_sel:DWORD src1_sel:WORD_1
	v_add_u32_e32 v28, v250, v132
	v_lshlrev_b32_sdwa v132, v215, v183 dst_sel:DWORD dst_unused:UNUSED_PAD src0_sel:DWORD src1_sel:WORD_1
	v_add_u32_e32 v30, v250, v132
	s_waitcnt lgkmcnt(1)
	v_lshlrev_b32_sdwa v132, v215, v184 dst_sel:DWORD dst_unused:UNUSED_PAD src0_sel:DWORD src1_sel:WORD_1
	v_add_u32_e32 v36, v250, v132
	v_lshlrev_b32_sdwa v132, v215, v185 dst_sel:DWORD dst_unused:UNUSED_PAD src0_sel:DWORD src1_sel:WORD_1
	global_load_dwordx4 v[4:7], v12, s[98:99]
	global_load_dwordx4 v[8:11], v14, s[98:99]
	s_nop 0
	global_load_dwordx4 v[12:15], v20, s[98:99]
	global_load_dwordx4 v[16:19], v22, s[98:99]
	s_nop 0
	global_load_dwordx4 v[20:23], v28, s[98:99]
	global_load_dwordx4 v[24:27], v30, s[98:99]
	v_add_u32_e32 v38, v250, v132
	global_load_dwordx4 v[28:31], v36, s[98:99]
	global_load_dwordx4 v[32:35], v38, s[98:99]
	ds_read2_b32 v[190:191], v212 offset0:144 offset1:152
	s_waitcnt lgkmcnt(1)
	v_lshlrev_b32_sdwa v132, v215, v186 dst_sel:DWORD dst_unused:UNUSED_PAD src0_sel:DWORD src1_sel:WORD_1
	v_add_u32_e32 v36, v250, v132
	v_lshlrev_b32_sdwa v132, v215, v187 dst_sel:DWORD dst_unused:UNUSED_PAD src0_sel:DWORD src1_sel:WORD_1
	v_add_u32_e32 v40, v250, v132
	s_waitcnt lgkmcnt(0)
	v_lshlrev_b32_sdwa v132, v215, v190 dst_sel:DWORD dst_unused:UNUSED_PAD src0_sel:DWORD src1_sel:WORD_1
	global_load_dwordx4 v[36:39], v36, s[98:99]
	s_nop 0
	global_load_dwordx4 v[40:43], v40, s[98:99]
	v_add_u32_e32 v44, v250, v132
	ds_read2_b32 v[192:193], v212 offset0:160 offset1:168
	v_lshlrev_b32_sdwa v132, v215, v191 dst_sel:DWORD dst_unused:UNUSED_PAD src0_sel:DWORD src1_sel:WORD_1
	v_add_u32_e32 v48, v250, v132
	global_load_dwordx4 v[44:47], v44, s[98:99]
	s_nop 0
	global_load_dwordx4 v[48:51], v48, s[98:99]
	ds_read2_b32 v[194:195], v212 offset0:176 offset1:184
	s_waitcnt lgkmcnt(1)
	v_lshlrev_b32_sdwa v132, v215, v192 dst_sel:DWORD dst_unused:UNUSED_PAD src0_sel:DWORD src1_sel:WORD_1
	v_add_u32_e32 v52, v250, v132
	v_lshlrev_b32_sdwa v132, v215, v193 dst_sel:DWORD dst_unused:UNUSED_PAD src0_sel:DWORD src1_sel:WORD_1
	v_add_u32_e32 v56, v250, v132
	s_waitcnt lgkmcnt(0)
	v_lshlrev_b32_sdwa v132, v215, v194 dst_sel:DWORD dst_unused:UNUSED_PAD src0_sel:DWORD src1_sel:WORD_1
	v_add_u32_e32 v60, v250, v132
	v_lshlrev_b32_sdwa v132, v215, v195 dst_sel:DWORD dst_unused:UNUSED_PAD src0_sel:DWORD src1_sel:WORD_1
	v_add_u32_e32 v64, v250, v132
	global_load_dwordx4 v[52:55], v52, s[98:99]
	s_nop 0
	global_load_dwordx4 v[56:59], v56, s[98:99]
	s_nop 0
	global_load_dwordx4 v[60:63], v60, s[98:99]
	s_nop 0
	global_load_dwordx4 v[64:67], v64, s[98:99]
	s_waitcnt vmcnt(44)
	ds_write2st64_b32 v213, v70, v71 offset0:3 offset1:4
	s_waitcnt vmcnt(42)
	ds_write2st64_b32 v213, v72, v73 offset0:5 offset1:6
	s_waitcnt vmcnt(40)
	ds_write2st64_b32 v213, v74, v75 offset0:7 offset1:8
	s_waitcnt vmcnt(38)
	ds_write2st64_b32 v213, v76, v77 offset0:9 offset1:10
	s_waitcnt vmcnt(36)
	ds_write2st64_b32 v213, v78, v79 offset0:11 offset1:12
	s_waitcnt vmcnt(34)
	ds_write2st64_b32 v213, v80, v81 offset0:13 offset1:14
	s_waitcnt vmcnt(32)
	ds_write2st64_b32 v213, v82, v83 offset0:15 offset1:16
	s_waitcnt vmcnt(30)
	ds_write2st64_b32 v213, v84, v85 offset0:17 offset1:18
	s_waitcnt vmcnt(28)
	ds_write2st64_b32 v213, v86, v87 offset0:19 offset1:20
	s_waitcnt vmcnt(26)
	ds_write2st64_b32 v213, v88, v89 offset0:21 offset1:22
	s_waitcnt vmcnt(24)
	ds_write2st64_b32 v213, v90, v91 offset0:23 offset1:24
	s_waitcnt vmcnt(22)
	ds_write2st64_b32 v213, v92, v93 offset0:25 offset1:26
	s_waitcnt vmcnt(20)
	ds_write2st64_b32 v213, v94, v95 offset0:27 offset1:28
	s_waitcnt vmcnt(18)
	ds_write2st64_b32 v213, v96, v97 offset0:29 offset1:30
	s_waitcnt vmcnt(16)
	ds_write2st64_b32 v213, v98, v99 offset0:31 offset1:32
	v_cndmask_b32_e32 v70, v161, v223, vcc
	v_cmp_lt_i32_e32 vcc, v224, v218
	v_lshlrev_b32_e32 v139, 2, v70
	s_nop 0
	v_cndmask_b32_e32 v70, v161, v224, vcc
	v_cmp_lt_i32_e32 vcc, v222, v218
	v_lshlrev_b32_e32 v141, 2, v70
	s_nop 0
	v_cndmask_b32_e32 v70, v161, v222, vcc
	v_lshlrev_b32_e32 v143, 2, v70
	s_branch .LBB0_1650

; DI void up_issue(u32x4 (&W)[16], u32 (&pj)[16], const u32* pl, const unsigned char* wbase, int grp) {
; #pragma unroll
;   for (int j = 0; j < 16; ++j) {
;     pj[j] = pl[8 * j + grp];
;     W[j] = *(const u32x4*)(wbase + (size_t)(pj[j] >> 16) * 1024);
;   }
; }
; DI void up_math(const u32x4 (&W)[16], const u32 (&pj)[16], float* __restrict__ yrow, int lane) {
;     ...
;   for (int j = 0; j < 16; ++j) {
;     const float h = __uint_as_float(pj[j] << 16);
;     const f2 hh = {h, h};
; #pragma unroll
;     for (int d = 0; d < 4; ++d) {
;       f2 lo = __builtin_amdgcn_cvt_pk_f32_fp8((int)W[j][d], false);
;       f2 hi = __builtin_amdgcn_cvt_pk_f32_fp8((int)W[j][d], true);
;       y[2 * d] = lo * hh + y[2 * d];
;       y[2 * d + 1] = hi * hh + y[2 * d + 1];
;     }
;   }
.LBB0_1650:
	ds_read2_b32 v[210:211], v145 offset1:8
	ds_read2_b32 v[208:209], v145 offset0:16 offset1:24
	s_waitcnt lgkmcnt(1)
	v_lshlrev_b32_sdwa v132, v215, v210 dst_sel:DWORD dst_unused:UNUSED_PAD src0_sel:DWORD src1_sel:WORD_1
	v_add_u32_e32 v68, v250, v132
	v_lshlrev_b32_sdwa v132, v215, v211 dst_sel:DWORD dst_unused:UNUSED_PAD src0_sel:DWORD src1_sel:WORD_1
	v_add_u32_e32 v70, v250, v132
	s_waitcnt lgkmcnt(0)
	v_lshlrev_b32_sdwa v132, v215, v208 dst_sel:DWORD dst_unused:UNUSED_PAD src0_sel:DWORD src1_sel:WORD_1
	global_load_dwordx4 v[128:131], v68, s[98:99]
	global_load_dwordx4 v[124:127], v70, s[98:99]
	ds_read2_b32 v[206:207], v145 offset0:32 offset1:40
	v_add_u32_e32 v68, v250, v132
	v_lshlrev_b32_sdwa v132, v215, v209 dst_sel:DWORD dst_unused:UNUSED_PAD src0_sel:DWORD src1_sel:WORD_1
	v_add_u32_e32 v70, v250, v132
	global_load_dwordx4 v[120:123], v68, s[98:99]
	global_load_dwordx4 v[116:119], v70, s[98:99]
	ds_read2_b32 v[204:205], v145 offset0:48 offset1:56
	s_waitcnt lgkmcnt(1)
	v_lshlrev_b32_sdwa v132, v215, v206 dst_sel:DWORD dst_unused:UNUSED_PAD src0_sel:DWORD src1_sel:WORD_1
	v_add_u32_e32 v68, v250, v132
	v_lshlrev_b32_sdwa v132, v215, v207 dst_sel:DWORD dst_unused:UNUSED_PAD src0_sel:DWORD src1_sel:WORD_1
	v_add_u32_e32 v70, v250, v132
	global_load_dwordx4 v[112:115], v68, s[98:99]
	global_load_dwordx4 v[108:111], v70, s[98:99]
	s_waitcnt lgkmcnt(0)
	v_lshlrev_b32_sdwa v132, v215, v204 dst_sel:DWORD dst_unused:UNUSED_PAD src0_sel:DWORD src1_sel:WORD_1
	ds_read2_b32 v[202:203], v145 offset0:64 offset1:72
	v_add_u32_e32 v68, v250, v132
	v_lshlrev_b32_sdwa v132, v215, v205 dst_sel:DWORD dst_unused:UNUSED_PAD src0_sel:DWORD src1_sel:WORD_1
	v_add_u32_e32 v70, v250, v132
	global_load_dwordx4 v[104:107], v68, s[98:99]
	global_load_dwordx4 v[100:103], v70, s[98:99]
	ds_read2_b32 v[200:201], v145 offset0:80 offset1:88
	s_waitcnt lgkmcnt(1)
	v_lshlrev_b32_sdwa v132, v215, v202 dst_sel:DWORD dst_unused:UNUSED_PAD src0_sel:DWORD src1_sel:WORD_1
	v_add_u32_e32 v68, v250, v132
	v_lshlrev_b32_sdwa v132, v215, v203 dst_sel:DWORD dst_unused:UNUSED_PAD src0_sel:DWORD src1_sel:WORD_1
	v_add_u32_e32 v70, v250, v132
	global_load_dwordx4 v[96:99], v68, s[98:99]
	global_load_dwordx4 v[92:95], v70, s[98:99]
	s_waitcnt lgkmcnt(0)
	v_lshlrev_b32_sdwa v132, v215, v200 dst_sel:DWORD dst_unused:UNUSED_PAD src0_sel:DWORD src1_sel:WORD_1
	ds_read2_b32 v[198:199], v145 offset0:96 offset1:104
	v_add_u32_e32 v68, v250, v132
	v_lshlrev_b32_sdwa v132, v215, v201 dst_sel:DWORD dst_unused:UNUSED_PAD src0_sel:DWORD src1_sel:WORD_1
	v_add_u32_e32 v70, v250, v132
	global_load_dwordx4 v[88:91], v68, s[98:99]
	global_load_dwordx4 v[84:87], v70, s[98:99]
	ds_read2_b32 v[196:197], v145 offset0:112 offset1:120
	s_waitcnt lgkmcnt(1)
	v_lshlrev_b32_sdwa v132, v215, v198 dst_sel:DWORD dst_unused:UNUSED_PAD src0_sel:DWORD src1_sel:WORD_1
	v_add_u32_e32 v68, v250, v132
	v_lshlrev_b32_sdwa v132, v215, v199 dst_sel:DWORD dst_unused:UNUSED_PAD src0_sel:DWORD src1_sel:WORD_1
	v_add_u32_e32 v70, v250, v132
	s_waitcnt lgkmcnt(0)
	v_lshlrev_b32_sdwa v132, v215, v196 dst_sel:DWORD dst_unused:UNUSED_PAD src0_sel:DWORD src1_sel:WORD_1
	global_load_dwordx4 v[80:83], v68, s[98:99]
	global_load_dwordx4 v[76:79], v70, s[98:99]
	v_add_u32_e32 v68, v250, v132
	v_lshlrev_b32_sdwa v132, v215, v197 dst_sel:DWORD dst_unused:UNUSED_PAD src0_sel:DWORD src1_sel:WORD_1
	v_add_u32_e32 v70, v250, v132
	global_load_dwordx4 v[72:75], v68, s[98:99]
	s_nop 0
	global_load_dwordx4 v[68:71], v70, s[98:99]
	s_waitcnt vmcnt(31)
	v_cvt_pk_f32_fp8_e32 v[216:217], v4
	v_cvt_pk_f32_fp8_sdwa v[226:227], v4 src0_sel:WORD_1
	v_cvt_pk_f32_fp8_e32 v[228:229], v5
	v_cvt_pk_f32_fp8_sdwa v[230:231], v5 src0_sel:WORD_1
	v_cvt_pk_f32_fp8_e32 v[232:233], v6
	v_cvt_pk_f32_fp8_sdwa v[234:235], v6 src0_sel:WORD_1
	v_cvt_pk_f32_fp8_e32 v[236:237], v7
	v_cvt_pk_f32_fp8_sdwa v[238:239], v7 src0_sel:WORD_1
	s_waitcnt vmcnt(30)
	v_cvt_pk_f32_fp8_e32 v[240:241], v8
	v_cvt_pk_f32_fp8_sdwa v[242:243], v8 src0_sel:WORD_1
	v_cvt_pk_f32_fp8_e32 v[244:245], v9
	v_cvt_pk_f32_fp8_sdwa v[246:247], v9 src0_sel:WORD_1
	v_lshlrev_b32_e32 v132, 16, v178
	v_pk_fma_f32 v[216:217], v[132:133], v[216:217], 0 op_sel_hi:[0,1,0]
	v_pk_fma_f32 v[226:227], v[132:133], v[226:227], 0 op_sel_hi:[0,1,0]
	v_pk_fma_f32 v[228:229], v[132:133], v[228:229], 0 op_sel_hi:[0,1,0]
	v_pk_fma_f32 v[230:231], v[132:133], v[230:231], 0 op_sel_hi:[0,1,0]
	v_pk_fma_f32 v[232:233], v[132:133], v[232:233], 0 op_sel_hi:[0,1,0]
	v_pk_fma_f32 v[234:235], v[132:133], v[234:235], 0 op_sel_hi:[0,1,0]
	v_pk_fma_f32 v[236:237], v[132:133], v[236:237], 0 op_sel_hi:[0,1,0]
	v_pk_fma_f32 v[238:239], v[132:133], v[238:239], 0 op_sel_hi:[0,1,0]
	v_lshlrev_b32_e32 v132, 16, v179
	v_pk_fma_f32 v[216:217], v[132:133], v[240:241], v[216:217] op_sel_hi:[0,1,1]
	v_cvt_pk_f32_fp8_e32 v[240:241], v10
	v_pk_fma_f32 v[226:227], v[132:133], v[242:243], v[226:227] op_sel_hi:[0,1,1]
	v_pk_fma_f32 v[228:229], v[132:133], v[244:245], v[228:229] op_sel_hi:[0,1,1]
	v_pk_fma_f32 v[230:231], v[132:133], v[246:247], v[230:231] op_sel_hi:[0,1,1]
	v_cvt_pk_f32_fp8_sdwa v[242:243], v10 src0_sel:WORD_1
	v_cvt_pk_f32_fp8_e32 v[244:245], v11
	v_cvt_pk_f32_fp8_sdwa v[246:247], v11 src0_sel:WORD_1
	v_pk_fma_f32 v[232:233], v[132:133], v[240:241], v[232:233] op_sel_hi:[0,1,1]
	s_waitcnt vmcnt(29)
; DI void up_math(const u32x4 (&W)[16], const u32 (&pj)[16], float* __restrict__ yrow, int lane) {
;     ...
;   for (int j = 0; j < 16; ++j) {
;     const float h = __uint_as_float(pj[j] << 16);
;     const f2 hh = {h, h};
; #pragma unroll
;     for (int d = 0; d < 4; ++d) {
;       f2 lo = __builtin_amdgcn_cvt_pk_f32_fp8((int)W[j][d], false);
;       f2 hi = __builtin_amdgcn_cvt_pk_f32_fp8((int)W[j][d], true);
;       y[2 * d] = lo * hh + y[2 * d];
;       y[2 * d + 1] = hi * hh + y[2 * d + 1];
;     }
;   }
	v_cvt_pk_f32_fp8_e32 v[240:241], v12
	v_pk_fma_f32 v[234:235], v[132:133], v[242:243], v[234:235] op_sel_hi:[0,1,1]
	v_pk_fma_f32 v[236:237], v[132:133], v[244:245], v[236:237] op_sel_hi:[0,1,1]
	v_pk_fma_f32 v[238:239], v[132:133], v[246:247], v[238:239] op_sel_hi:[0,1,1]
	v_cvt_pk_f32_fp8_sdwa v[242:243], v12 src0_sel:WORD_1
	v_cvt_pk_f32_fp8_e32 v[244:245], v13
	v_cvt_pk_f32_fp8_sdwa v[246:247], v13 src0_sel:WORD_1
	v_lshlrev_b32_e32 v132, 16, v180
	v_pk_fma_f32 v[216:217], v[132:133], v[240:241], v[216:217] op_sel_hi:[0,1,1]
	v_cvt_pk_f32_fp8_e32 v[240:241], v14
	v_pk_fma_f32 v[226:227], v[132:133], v[242:243], v[226:227] op_sel_hi:[0,1,1]
	v_pk_fma_f32 v[228:229], v[132:133], v[244:245], v[228:229] op_sel_hi:[0,1,1]
	v_pk_fma_f32 v[230:231], v[132:133], v[246:247], v[230:231] op_sel_hi:[0,1,1]
	v_cvt_pk_f32_fp8_sdwa v[242:243], v14 src0_sel:WORD_1
	v_cvt_pk_f32_fp8_e32 v[244:245], v15
	v_cvt_pk_f32_fp8_sdwa v[246:247], v15 src0_sel:WORD_1
	v_pk_fma_f32 v[232:233], v[132:133], v[240:241], v[232:233] op_sel_hi:[0,1,1]
	s_waitcnt vmcnt(28)
	v_cvt_pk_f32_fp8_e32 v[240:241], v16
	v_pk_fma_f32 v[234:235], v[132:133], v[242:243], v[234:235] op_sel_hi:[0,1,1]
	v_pk_fma_f32 v[236:237], v[132:133], v[244:245], v[236:237] op_sel_hi:[0,1,1]
	v_pk_fma_f32 v[238:239], v[132:133], v[246:247], v[238:239] op_sel_hi:[0,1,1]
	v_cvt_pk_f32_fp8_sdwa v[242:243], v16 src0_sel:WORD_1
	v_cvt_pk_f32_fp8_e32 v[244:245], v17
	v_cvt_pk_f32_fp8_sdwa v[246:247], v17 src0_sel:WORD_1
	v_lshlrev_b32_e32 v132, 16, v181
	v_pk_fma_f32 v[216:217], v[132:133], v[240:241], v[216:217] op_sel_hi:[0,1,1]
	v_cvt_pk_f32_fp8_e32 v[240:241], v18
	v_pk_fma_f32 v[226:227], v[132:133], v[242:243], v[226:227] op_sel_hi:[0,1,1]
	v_pk_fma_f32 v[228:229], v[132:133], v[244:245], v[228:229] op_sel_hi:[0,1,1]
	v_pk_fma_f32 v[230:231], v[132:133], v[246:247], v[230:231] op_sel_hi:[0,1,1]
	v_cvt_pk_f32_fp8_sdwa v[242:243], v18 src0_sel:WORD_1
	v_cvt_pk_f32_fp8_e32 v[244:245], v19
	v_cvt_pk_f32_fp8_sdwa v[246:247], v19 src0_sel:WORD_1
	v_pk_fma_f32 v[232:233], v[132:133], v[240:241], v[232:233] op_sel_hi:[0,1,1]
	s_waitcnt vmcnt(27)
	v_cvt_pk_f32_fp8_e32 v[240:241], v20
	v_pk_fma_f32 v[234:235], v[132:133], v[242:243], v[234:235] op_sel_hi:[0,1,1]
	v_pk_fma_f32 v[236:237], v[132:133], v[244:245], v[236:237] op_sel_hi:[0,1,1]
	v_pk_fma_f32 v[238:239], v[132:133], v[246:247], v[238:239] op_sel_hi:[0,1,1]
	v_cvt_pk_f32_fp8_sdwa v[242:243], v20 src0_sel:WORD_1
	v_cvt_pk_f32_fp8_e32 v[244:245], v21
	v_cvt_pk_f32_fp8_sdwa v[246:247], v21 src0_sel:WORD_1
	v_lshlrev_b32_e32 v132, 16, v182
	v_pk_fma_f32 v[216:217], v[132:133], v[240:241], v[216:217] op_sel_hi:[0,1,1]
	v_cvt_pk_f32_fp8_e32 v[240:241], v22
	v_pk_fma_f32 v[226:227], v[132:133], v[242:243], v[226:227] op_sel_hi:[0,1,1]
	v_pk_fma_f32 v[228:229], v[132:133], v[244:245], v[228:229] op_sel_hi:[0,1,1]
	v_pk_fma_f32 v[230:231], v[132:133], v[246:247], v[230:231] op_sel_hi:[0,1,1]
	v_cvt_pk_f32_fp8_sdwa v[242:243], v22 src0_sel:WORD_1
	v_cvt_pk_f32_fp8_e32 v[244:245], v23
	v_cvt_pk_f32_fp8_sdwa v[246:247], v23 src0_sel:WORD_1
	v_pk_fma_f32 v[232:233], v[132:133], v[240:241], v[232:233] op_sel_hi:[0,1,1]
	s_waitcnt vmcnt(26)
	v_cvt_pk_f32_fp8_e32 v[240:241], v24
	v_pk_fma_f32 v[234:235], v[132:133], v[242:243], v[234:235] op_sel_hi:[0,1,1]
	v_pk_fma_f32 v[236:237], v[132:133], v[244:245], v[236:237] op_sel_hi:[0,1,1]
	v_pk_fma_f32 v[238:239], v[132:133], v[246:247], v[238:239] op_sel_hi:[0,1,1]
	v_cvt_pk_f32_fp8_sdwa v[242:243], v24 src0_sel:WORD_1
	v_cvt_pk_f32_fp8_e32 v[244:245], v25
	v_cvt_pk_f32_fp8_sdwa v[246:247], v25 src0_sel:WORD_1
	v_lshlrev_b32_e32 v132, 16, v183
	v_pk_fma_f32 v[216:217], v[132:133], v[240:241], v[216:217] op_sel_hi:[0,1,1]
	v_cvt_pk_f32_fp8_e32 v[240:241], v26
	v_pk_fma_f32 v[226:227], v[132:133], v[242:243], v[226:227] op_sel_hi:[0,1,1]
	v_pk_fma_f32 v[228:229], v[132:133], v[244:245], v[228:229] op_sel_hi:[0,1,1]
	v_pk_fma_f32 v[230:231], v[132:133], v[246:247], v[230:231] op_sel_hi:[0,1,1]
	v_cvt_pk_f32_fp8_sdwa v[242:243], v26 src0_sel:WORD_1
	v_cvt_pk_f32_fp8_e32 v[244:245], v27
	v_cvt_pk_f32_fp8_sdwa v[246:247], v27 src0_sel:WORD_1
	v_pk_fma_f32 v[232:233], v[132:133], v[240:241], v[232:233] op_sel_hi:[0,1,1]
	s_waitcnt vmcnt(25)
	v_cvt_pk_f32_fp8_e32 v[240:241], v28
	v_pk_fma_f32 v[234:235], v[132:133], v[242:243], v[234:235] op_sel_hi:[0,1,1]
	v_pk_fma_f32 v[236:237], v[132:133], v[244:245], v[236:237] op_sel_hi:[0,1,1]
	v_pk_fma_f32 v[238:239], v[132:133], v[246:247], v[238:239] op_sel_hi:[0,1,1]
	v_cvt_pk_f32_fp8_sdwa v[242:243], v28 src0_sel:WORD_1
	v_cvt_pk_f32_fp8_e32 v[244:245], v29
	v_cvt_pk_f32_fp8_sdwa v[246:247], v29 src0_sel:WORD_1
	v_lshlrev_b32_e32 v132, 16, v184
	v_pk_fma_f32 v[216:217], v[132:133], v[240:241], v[216:217] op_sel_hi:[0,1,1]
	v_cvt_pk_f32_fp8_e32 v[240:241], v30
	v_pk_fma_f32 v[226:227], v[132:133], v[242:243], v[226:227] op_sel_hi:[0,1,1]
	v_pk_fma_f32 v[228:229], v[132:133], v[244:245], v[228:229] op_sel_hi:[0,1,1]
	v_pk_fma_f32 v[230:231], v[132:133], v[246:247], v[230:231] op_sel_hi:[0,1,1]
	v_cvt_pk_f32_fp8_sdwa v[242:243], v30 src0_sel:WORD_1
	v_cvt_pk_f32_fp8_e32 v[244:245], v31
	v_cvt_pk_f32_fp8_sdwa v[246:247], v31 src0_sel:WORD_1
	v_pk_fma_f32 v[232:233], v[132:133], v[240:241], v[232:233] op_sel_hi:[0,1,1]
	s_waitcnt vmcnt(24)
; DI void up_math(const u32x4 (&W)[16], const u32 (&pj)[16], float* __restrict__ yrow, int lane) {
;     ...
;   for (int j = 0; j < 16; ++j) {
;     const float h = __uint_as_float(pj[j] << 16);
;     const f2 hh = {h, h};
; #pragma unroll
;     for (int d = 0; d < 4; ++d) {
;       f2 lo = __builtin_amdgcn_cvt_pk_f32_fp8((int)W[j][d], false);
;       f2 hi = __builtin_amdgcn_cvt_pk_f32_fp8((int)W[j][d], true);
;       y[2 * d] = lo * hh + y[2 * d];
;       y[2 * d + 1] = hi * hh + y[2 * d + 1];
;     }
;   }
	v_cvt_pk_f32_fp8_e32 v[240:241], v32
	v_pk_fma_f32 v[234:235], v[132:133], v[242:243], v[234:235] op_sel_hi:[0,1,1]
	v_pk_fma_f32 v[236:237], v[132:133], v[244:245], v[236:237] op_sel_hi:[0,1,1]
	v_pk_fma_f32 v[238:239], v[132:133], v[246:247], v[238:239] op_sel_hi:[0,1,1]
	v_cvt_pk_f32_fp8_sdwa v[242:243], v32 src0_sel:WORD_1
	v_cvt_pk_f32_fp8_e32 v[244:245], v33
	v_cvt_pk_f32_fp8_sdwa v[246:247], v33 src0_sel:WORD_1
	v_lshlrev_b32_e32 v132, 16, v185
	v_pk_fma_f32 v[216:217], v[132:133], v[240:241], v[216:217] op_sel_hi:[0,1,1]
	v_cvt_pk_f32_fp8_e32 v[240:241], v34
	v_pk_fma_f32 v[226:227], v[132:133], v[242:243], v[226:227] op_sel_hi:[0,1,1]
	v_pk_fma_f32 v[228:229], v[132:133], v[244:245], v[228:229] op_sel_hi:[0,1,1]
	v_pk_fma_f32 v[230:231], v[132:133], v[246:247], v[230:231] op_sel_hi:[0,1,1]
	v_cvt_pk_f32_fp8_sdwa v[242:243], v34 src0_sel:WORD_1
	v_cvt_pk_f32_fp8_e32 v[244:245], v35
	v_cvt_pk_f32_fp8_sdwa v[246:247], v35 src0_sel:WORD_1
	v_pk_fma_f32 v[232:233], v[132:133], v[240:241], v[232:233] op_sel_hi:[0,1,1]
	s_waitcnt vmcnt(23)
	v_cvt_pk_f32_fp8_e32 v[240:241], v36
	v_pk_fma_f32 v[234:235], v[132:133], v[242:243], v[234:235] op_sel_hi:[0,1,1]
	v_pk_fma_f32 v[236:237], v[132:133], v[244:245], v[236:237] op_sel_hi:[0,1,1]
	v_pk_fma_f32 v[238:239], v[132:133], v[246:247], v[238:239] op_sel_hi:[0,1,1]
	v_cvt_pk_f32_fp8_sdwa v[242:243], v36 src0_sel:WORD_1
	v_cvt_pk_f32_fp8_e32 v[244:245], v37
	v_cvt_pk_f32_fp8_sdwa v[246:247], v37 src0_sel:WORD_1
	v_lshlrev_b32_e32 v132, 16, v186
	v_pk_fma_f32 v[216:217], v[132:133], v[240:241], v[216:217] op_sel_hi:[0,1,1]
	v_cvt_pk_f32_fp8_e32 v[240:241], v38
	v_pk_fma_f32 v[226:227], v[132:133], v[242:243], v[226:227] op_sel_hi:[0,1,1]
	v_pk_fma_f32 v[228:229], v[132:133], v[244:245], v[228:229] op_sel_hi:[0,1,1]
	v_pk_fma_f32 v[230:231], v[132:133], v[246:247], v[230:231] op_sel_hi:[0,1,1]
	v_cvt_pk_f32_fp8_sdwa v[242:243], v38 src0_sel:WORD_1
	v_cvt_pk_f32_fp8_e32 v[244:245], v39
	v_cvt_pk_f32_fp8_sdwa v[246:247], v39 src0_sel:WORD_1
	v_pk_fma_f32 v[232:233], v[132:133], v[240:241], v[232:233] op_sel_hi:[0,1,1]
	s_waitcnt vmcnt(22)
	v_cvt_pk_f32_fp8_e32 v[240:241], v40
	v_pk_fma_f32 v[234:235], v[132:133], v[242:243], v[234:235] op_sel_hi:[0,1,1]
	v_pk_fma_f32 v[236:237], v[132:133], v[244:245], v[236:237] op_sel_hi:[0,1,1]
	v_pk_fma_f32 v[238:239], v[132:133], v[246:247], v[238:239] op_sel_hi:[0,1,1]
	v_cvt_pk_f32_fp8_sdwa v[242:243], v40 src0_sel:WORD_1
	v_cvt_pk_f32_fp8_e32 v[244:245], v41
	v_cvt_pk_f32_fp8_sdwa v[246:247], v41 src0_sel:WORD_1
	v_lshlrev_b32_e32 v132, 16, v187
	v_pk_fma_f32 v[216:217], v[132:133], v[240:241], v[216:217] op_sel_hi:[0,1,1]
	v_cvt_pk_f32_fp8_e32 v[240:241], v42
	v_pk_fma_f32 v[226:227], v[132:133], v[242:243], v[226:227] op_sel_hi:[0,1,1]
	v_pk_fma_f32 v[228:229], v[132:133], v[244:245], v[228:229] op_sel_hi:[0,1,1]
	v_pk_fma_f32 v[230:231], v[132:133], v[246:247], v[230:231] op_sel_hi:[0,1,1]
	v_cvt_pk_f32_fp8_sdwa v[242:243], v42 src0_sel:WORD_1
	v_cvt_pk_f32_fp8_e32 v[244:245], v43
	v_cvt_pk_f32_fp8_sdwa v[246:247], v43 src0_sel:WORD_1
	v_pk_fma_f32 v[232:233], v[132:133], v[240:241], v[232:233] op_sel_hi:[0,1,1]
	s_waitcnt vmcnt(21)
	v_cvt_pk_f32_fp8_e32 v[240:241], v44
	v_pk_fma_f32 v[234:235], v[132:133], v[242:243], v[234:235] op_sel_hi:[0,1,1]
	v_pk_fma_f32 v[236:237], v[132:133], v[244:245], v[236:237] op_sel_hi:[0,1,1]
	v_pk_fma_f32 v[238:239], v[132:133], v[246:247], v[238:239] op_sel_hi:[0,1,1]
	v_cvt_pk_f32_fp8_sdwa v[242:243], v44 src0_sel:WORD_1
	v_cvt_pk_f32_fp8_e32 v[244:245], v45
	v_cvt_pk_f32_fp8_sdwa v[246:247], v45 src0_sel:WORD_1
	v_lshlrev_b32_e32 v132, 16, v190
	v_pk_fma_f32 v[216:217], v[132:133], v[240:241], v[216:217] op_sel_hi:[0,1,1]
	v_cvt_pk_f32_fp8_e32 v[240:241], v46
	v_pk_fma_f32 v[226:227], v[132:133], v[242:243], v[226:227] op_sel_hi:[0,1,1]
	v_pk_fma_f32 v[228:229], v[132:133], v[244:245], v[228:229] op_sel_hi:[0,1,1]
	v_pk_fma_f32 v[230:231], v[132:133], v[246:247], v[230:231] op_sel_hi:[0,1,1]
	v_cvt_pk_f32_fp8_sdwa v[242:243], v46 src0_sel:WORD_1
	v_cvt_pk_f32_fp8_e32 v[244:245], v47
	v_cvt_pk_f32_fp8_sdwa v[246:247], v47 src0_sel:WORD_1
	v_pk_fma_f32 v[232:233], v[132:133], v[240:241], v[232:233] op_sel_hi:[0,1,1]
	s_waitcnt vmcnt(20)
	v_cvt_pk_f32_fp8_e32 v[240:241], v48
	v_pk_fma_f32 v[234:235], v[132:133], v[242:243], v[234:235] op_sel_hi:[0,1,1]
	v_pk_fma_f32 v[236:237], v[132:133], v[244:245], v[236:237] op_sel_hi:[0,1,1]
	v_pk_fma_f32 v[238:239], v[132:133], v[246:247], v[238:239] op_sel_hi:[0,1,1]
	v_cvt_pk_f32_fp8_sdwa v[242:243], v48 src0_sel:WORD_1
	v_cvt_pk_f32_fp8_e32 v[244:245], v49
	v_cvt_pk_f32_fp8_sdwa v[246:247], v49 src0_sel:WORD_1
	v_lshlrev_b32_e32 v132, 16, v191
	v_pk_fma_f32 v[216:217], v[132:133], v[240:241], v[216:217] op_sel_hi:[0,1,1]
	v_cvt_pk_f32_fp8_e32 v[240:241], v50
	v_pk_fma_f32 v[226:227], v[132:133], v[242:243], v[226:227] op_sel_hi:[0,1,1]
	v_pk_fma_f32 v[228:229], v[132:133], v[244:245], v[228:229] op_sel_hi:[0,1,1]
	v_pk_fma_f32 v[230:231], v[132:133], v[246:247], v[230:231] op_sel_hi:[0,1,1]
	v_cvt_pk_f32_fp8_sdwa v[242:243], v50 src0_sel:WORD_1
	v_cvt_pk_f32_fp8_e32 v[244:245], v51
	v_cvt_pk_f32_fp8_sdwa v[246:247], v51 src0_sel:WORD_1
	v_pk_fma_f32 v[232:233], v[132:133], v[240:241], v[232:233] op_sel_hi:[0,1,1]
	s_waitcnt vmcnt(19)
; DI void up_math(const u32x4 (&W)[16], const u32 (&pj)[16], float* __restrict__ yrow, int lane) {
;     ...
;   for (int j = 0; j < 16; ++j) {
;     const float h = __uint_as_float(pj[j] << 16);
;     const f2 hh = {h, h};
; #pragma unroll
;     for (int d = 0; d < 4; ++d) {
;       f2 lo = __builtin_amdgcn_cvt_pk_f32_fp8((int)W[j][d], false);
;       f2 hi = __builtin_amdgcn_cvt_pk_f32_fp8((int)W[j][d], true);
;       y[2 * d] = lo * hh + y[2 * d];
;       y[2 * d + 1] = hi * hh + y[2 * d + 1];
;     }
;   }
;   const bool b5 = lane & 32, b4 = lane & 16, b3 = lane & 8;
;   f2 q4[4];
; #pragma unroll
;   for (int i = 0; i < 4; ++i) {
;     f2 snd = b5 ? y[i] : y[i + 4]; f2 kp = b5 ? y[i + 4] : y[i];
;     q4[i] = f2{kp.x + __shfl_xor(snd.x, 32), kp.y + __shfl_xor(snd.y, 32)};
;   }
;   f2 r2[2];
; #pragma unroll
;   for (int i = 0; i < 2; ++i) {
;     f2 snd = b4 ? q4[i] : q4[i + 2]; f2 kp = b4 ? q4[i + 2] : q4[i];
;     r2[i] = f2{kp.x + __shfl_xor(snd.x, 16), kp.y + __shfl_xor(snd.y, 16)};
;   }
;   f2 a;
;   { f2 snd = b3 ? r2[0] : r2[1]; f2 kp = b3 ? r2[1] : r2[0]; a = f2{kp.x + __shfl_xor(snd.x, 8), kp.y + __shfl_xor(snd.y, 8)}; }
;   const int ci = (b5 ? 4 : 0) + (b4 ? 2 : 0) + (b3 ? 1 : 0);
;   *(float2*)(yrow + (lane & 7) * 16 + 2 * ci) = make_float2(a.x, a.y);
	v_cvt_pk_f32_fp8_e32 v[240:241], v52
	v_pk_fma_f32 v[234:235], v[132:133], v[242:243], v[234:235] op_sel_hi:[0,1,1]
	v_pk_fma_f32 v[236:237], v[132:133], v[244:245], v[236:237] op_sel_hi:[0,1,1]
	v_pk_fma_f32 v[238:239], v[132:133], v[246:247], v[238:239] op_sel_hi:[0,1,1]
	v_cvt_pk_f32_fp8_sdwa v[242:243], v52 src0_sel:WORD_1
	v_cvt_pk_f32_fp8_e32 v[244:245], v53
	v_cvt_pk_f32_fp8_sdwa v[246:247], v53 src0_sel:WORD_1
	v_lshlrev_b32_e32 v132, 16, v192
	v_pk_fma_f32 v[216:217], v[132:133], v[240:241], v[216:217] op_sel_hi:[0,1,1]
	v_cvt_pk_f32_fp8_e32 v[240:241], v54
	v_pk_fma_f32 v[226:227], v[132:133], v[242:243], v[226:227] op_sel_hi:[0,1,1]
	v_pk_fma_f32 v[228:229], v[132:133], v[244:245], v[228:229] op_sel_hi:[0,1,1]
	v_pk_fma_f32 v[230:231], v[132:133], v[246:247], v[230:231] op_sel_hi:[0,1,1]
	v_cvt_pk_f32_fp8_sdwa v[242:243], v54 src0_sel:WORD_1
	v_cvt_pk_f32_fp8_e32 v[244:245], v55
	v_cvt_pk_f32_fp8_sdwa v[246:247], v55 src0_sel:WORD_1
	v_pk_fma_f32 v[232:233], v[132:133], v[240:241], v[232:233] op_sel_hi:[0,1,1]
	s_waitcnt vmcnt(18)
	v_cvt_pk_f32_fp8_e32 v[240:241], v56
	v_pk_fma_f32 v[234:235], v[132:133], v[242:243], v[234:235] op_sel_hi:[0,1,1]
	v_pk_fma_f32 v[236:237], v[132:133], v[244:245], v[236:237] op_sel_hi:[0,1,1]
	v_pk_fma_f32 v[238:239], v[132:133], v[246:247], v[238:239] op_sel_hi:[0,1,1]
	v_cvt_pk_f32_fp8_sdwa v[242:243], v56 src0_sel:WORD_1
	v_cvt_pk_f32_fp8_e32 v[244:245], v57
	v_cvt_pk_f32_fp8_sdwa v[246:247], v57 src0_sel:WORD_1
	v_lshlrev_b32_e32 v132, 16, v193
	v_pk_fma_f32 v[216:217], v[132:133], v[240:241], v[216:217] op_sel_hi:[0,1,1]
	v_cvt_pk_f32_fp8_e32 v[240:241], v58
	v_pk_fma_f32 v[226:227], v[132:133], v[242:243], v[226:227] op_sel_hi:[0,1,1]
	v_pk_fma_f32 v[228:229], v[132:133], v[244:245], v[228:229] op_sel_hi:[0,1,1]
	v_pk_fma_f32 v[230:231], v[132:133], v[246:247], v[230:231] op_sel_hi:[0,1,1]
	v_cvt_pk_f32_fp8_sdwa v[242:243], v58 src0_sel:WORD_1
	v_cvt_pk_f32_fp8_e32 v[244:245], v59
	v_cvt_pk_f32_fp8_sdwa v[246:247], v59 src0_sel:WORD_1
	v_pk_fma_f32 v[232:233], v[132:133], v[240:241], v[232:233] op_sel_hi:[0,1,1]
	s_waitcnt vmcnt(17)
	v_cvt_pk_f32_fp8_e32 v[240:241], v60
	v_pk_fma_f32 v[234:235], v[132:133], v[242:243], v[234:235] op_sel_hi:[0,1,1]
	v_pk_fma_f32 v[236:237], v[132:133], v[244:245], v[236:237] op_sel_hi:[0,1,1]
	v_pk_fma_f32 v[238:239], v[132:133], v[246:247], v[238:239] op_sel_hi:[0,1,1]
	v_cvt_pk_f32_fp8_sdwa v[242:243], v60 src0_sel:WORD_1
	v_cvt_pk_f32_fp8_e32 v[244:245], v61
	v_cvt_pk_f32_fp8_sdwa v[246:247], v61 src0_sel:WORD_1
	v_lshlrev_b32_e32 v132, 16, v194
	v_pk_fma_f32 v[216:217], v[132:133], v[240:241], v[216:217] op_sel_hi:[0,1,1]
	v_cvt_pk_f32_fp8_e32 v[240:241], v62
	v_pk_fma_f32 v[226:227], v[132:133], v[242:243], v[226:227] op_sel_hi:[0,1,1]
	v_pk_fma_f32 v[228:229], v[132:133], v[244:245], v[228:229] op_sel_hi:[0,1,1]
	v_pk_fma_f32 v[230:231], v[132:133], v[246:247], v[230:231] op_sel_hi:[0,1,1]
	v_cvt_pk_f32_fp8_sdwa v[242:243], v62 src0_sel:WORD_1
	v_cvt_pk_f32_fp8_e32 v[244:245], v63
	v_cvt_pk_f32_fp8_sdwa v[246:247], v63 src0_sel:WORD_1
	v_pk_fma_f32 v[232:233], v[132:133], v[240:241], v[232:233] op_sel_hi:[0,1,1]
	s_waitcnt vmcnt(16)
	v_cvt_pk_f32_fp8_e32 v[240:241], v64
	v_pk_fma_f32 v[234:235], v[132:133], v[242:243], v[234:235] op_sel_hi:[0,1,1]
	v_pk_fma_f32 v[236:237], v[132:133], v[244:245], v[236:237] op_sel_hi:[0,1,1]
	v_pk_fma_f32 v[238:239], v[132:133], v[246:247], v[238:239] op_sel_hi:[0,1,1]
	v_cvt_pk_f32_fp8_sdwa v[242:243], v64 src0_sel:WORD_1
	v_cvt_pk_f32_fp8_e32 v[244:245], v65
	v_cvt_pk_f32_fp8_sdwa v[246:247], v65 src0_sel:WORD_1
	v_lshlrev_b32_e32 v132, 16, v195
	v_pk_fma_f32 v[216:217], v[132:133], v[240:241], v[216:217] op_sel_hi:[0,1,1]
	v_cvt_pk_f32_fp8_e32 v[240:241], v66
	v_pk_fma_f32 v[226:227], v[132:133], v[242:243], v[226:227] op_sel_hi:[0,1,1]
	v_pk_fma_f32 v[228:229], v[132:133], v[244:245], v[228:229] op_sel_hi:[0,1,1]
	v_pk_fma_f32 v[230:231], v[132:133], v[246:247], v[230:231] op_sel_hi:[0,1,1]
	v_cvt_pk_f32_fp8_sdwa v[242:243], v66 src0_sel:WORD_1
	v_cvt_pk_f32_fp8_e32 v[244:245], v67
	v_cvt_pk_f32_fp8_sdwa v[246:247], v67 src0_sel:WORD_1
	v_pk_fma_f32 v[232:233], v[132:133], v[240:241], v[232:233] op_sel_hi:[0,1,1]
	v_pk_fma_f32 v[234:235], v[132:133], v[242:243], v[234:235] op_sel_hi:[0,1,1]
	v_pk_fma_f32 v[236:237], v[132:133], v[244:245], v[236:237] op_sel_hi:[0,1,1]
	v_pk_fma_f32 v[238:239], v[132:133], v[246:247], v[238:239] op_sel_hi:[0,1,1]
	s_nop 1
	v_permlane32_swap_b32_e32 v216, v232
	v_permlane32_swap_b32_e32 v217, v233
	v_permlane32_swap_b32_e32 v228, v236
	v_permlane32_swap_b32_e32 v229, v237
	v_permlane32_swap_b32_e32 v226, v234
	v_permlane32_swap_b32_e32 v227, v235
	v_permlane32_swap_b32_e32 v230, v238
	v_permlane32_swap_b32_e32 v231, v239
	v_pk_add_f32 v[216:217], v[216:217], v[232:233]
	v_pk_add_f32 v[228:229], v[228:229], v[236:237]
	v_pk_add_f32 v[226:227], v[226:227], v[234:235]
	v_pk_add_f32 v[230:231], v[230:231], v[238:239]
	s_nop 1
	v_permlane16_swap_b32_e32 v216, v228
	v_permlane16_swap_b32_e32 v217, v229
	v_permlane16_swap_b32_e32 v226, v230
	v_permlane16_swap_b32_e32 v227, v231
	v_pk_add_f32 v[216:217], v[216:217], v[228:229]
	v_pk_add_f32 v[226:227], v[226:227], v[230:231]
	s_nop 0
	v_cndmask_b32_e64 v132, v217, v227, s[10:11]
	v_cndmask_b32_e64 v147, v216, v226, s[10:11]
	ds_bpermute_b32 v228, v143, v147
	ds_bpermute_b32 v229, v143, v132
	v_cndmask_b32_e64 v217, v227, v217, s[10:11]
	v_cndmask_b32_e64 v216, v226, v216, s[10:11]
	s_waitcnt lgkmcnt(0)
	v_pk_add_f32 v[216:217], v[216:217], v[228:229]
	global_store_dwordx2 v[188:189], v[216:217], off
	s_cmp_gt_u32 s36, 13
	s_cselect_b64 s[28:29], -1, 0
	s_and_b64 vcc, exec, s[28:29]
	s_cbranch_vccnz .LBB0_1649
; DI void up_issue(u32x4 (&W)[16], u32 (&pj)[16], const u32* pl, const unsigned char* wbase, int grp) {
; #pragma unroll
;   for (int j = 0; j < 16; ++j) {
;     pj[j] = pl[8 * j + grp];
;     W[j] = *(const u32x4*)(wbase + (size_t)(pj[j] >> 16) * 1024);
;   }
; }
	ds_read2_b32 v[178:179], v145 offset0:128 offset1:136
	ds_read2_b32 v[180:181], v145 offset0:144 offset1:152
	s_waitcnt lgkmcnt(1)
	v_lshlrev_b32_sdwa v132, v215, v178 dst_sel:DWORD dst_unused:UNUSED_PAD src0_sel:DWORD src1_sel:WORD_1
	v_add_u32_e32 v4, v250, v132
	v_lshlrev_b32_sdwa v132, v215, v179 dst_sel:DWORD dst_unused:UNUSED_PAD src0_sel:DWORD src1_sel:WORD_1
	v_add_u32_e32 v8, v250, v132
	s_waitcnt lgkmcnt(0)
	v_lshlrev_b32_sdwa v132, v215, v180 dst_sel:DWORD dst_unused:UNUSED_PAD src0_sel:DWORD src1_sel:WORD_1
	global_load_dwordx4 v[4:7], v4, s[98:99]
	s_nop 0
	global_load_dwordx4 v[8:11], v8, s[98:99]
	v_add_u32_e32 v12, v250, v132
	ds_read2_b32 v[182:183], v145 offset0:160 offset1:168
	v_lshlrev_b32_sdwa v132, v215, v181 dst_sel:DWORD dst_unused:UNUSED_PAD src0_sel:DWORD src1_sel:WORD_1
	v_add_u32_e32 v16, v250, v132
	global_load_dwordx4 v[12:15], v12, s[98:99]
	s_nop 0
	global_load_dwordx4 v[16:19], v16, s[98:99]
	ds_read2_b32 v[184:185], v145 offset0:176 offset1:184
	s_waitcnt lgkmcnt(1)
	v_lshlrev_b32_sdwa v132, v215, v182 dst_sel:DWORD dst_unused:UNUSED_PAD src0_sel:DWORD src1_sel:WORD_1
	v_add_u32_e32 v20, v250, v132
	v_lshlrev_b32_sdwa v132, v215, v183 dst_sel:DWORD dst_unused:UNUSED_PAD src0_sel:DWORD src1_sel:WORD_1
	v_add_u32_e32 v24, v250, v132
	s_waitcnt lgkmcnt(0)
	v_lshlrev_b32_sdwa v132, v215, v184 dst_sel:DWORD dst_unused:UNUSED_PAD src0_sel:DWORD src1_sel:WORD_1
	global_load_dwordx4 v[20:23], v20, s[98:99]
	s_nop 0
	global_load_dwordx4 v[24:27], v24, s[98:99]
	v_add_u32_e32 v28, v250, v132
	ds_read2_b32 v[186:187], v145 offset0:192 offset1:200
	v_lshlrev_b32_sdwa v132, v215, v185 dst_sel:DWORD dst_unused:UNUSED_PAD src0_sel:DWORD src1_sel:WORD_1
	v_add_u32_e32 v32, v250, v132
	global_load_dwordx4 v[28:31], v28, s[98:99]
	s_nop 0
	global_load_dwordx4 v[32:35], v32, s[98:99]
	ds_read2_b32 v[190:191], v145 offset0:208 offset1:216
	s_waitcnt lgkmcnt(1)
	v_lshlrev_b32_sdwa v132, v215, v186 dst_sel:DWORD dst_unused:UNUSED_PAD src0_sel:DWORD src1_sel:WORD_1
	v_add_u32_e32 v36, v250, v132
	v_lshlrev_b32_sdwa v132, v215, v187 dst_sel:DWORD dst_unused:UNUSED_PAD src0_sel:DWORD src1_sel:WORD_1
	v_add_u32_e32 v40, v250, v132
	s_waitcnt lgkmcnt(0)
	v_lshlrev_b32_sdwa v132, v215, v190 dst_sel:DWORD dst_unused:UNUSED_PAD src0_sel:DWORD src1_sel:WORD_1
	global_load_dwordx4 v[36:39], v36, s[98:99]
	s_nop 0
	global_load_dwordx4 v[40:43], v40, s[98:99]
	v_add_u32_e32 v44, v250, v132
	ds_read2_b32 v[192:193], v145 offset0:224 offset1:232
	v_lshlrev_b32_sdwa v132, v215, v191 dst_sel:DWORD dst_unused:UNUSED_PAD src0_sel:DWORD src1_sel:WORD_1
	v_add_u32_e32 v48, v250, v132
	global_load_dwordx4 v[44:47], v44, s[98:99]
	s_nop 0
	global_load_dwordx4 v[48:51], v48, s[98:99]
	ds_read2_b32 v[194:195], v145 offset0:240 offset1:248
	s_waitcnt lgkmcnt(1)
	v_lshlrev_b32_sdwa v132, v215, v192 dst_sel:DWORD dst_unused:UNUSED_PAD src0_sel:DWORD src1_sel:WORD_1
	v_add_u32_e32 v52, v250, v132
	v_lshlrev_b32_sdwa v132, v215, v193 dst_sel:DWORD dst_unused:UNUSED_PAD src0_sel:DWORD src1_sel:WORD_1
	v_add_u32_e32 v56, v250, v132
	s_waitcnt lgkmcnt(0)
	v_lshlrev_b32_sdwa v132, v215, v194 dst_sel:DWORD dst_unused:UNUSED_PAD src0_sel:DWORD src1_sel:WORD_1
	v_add_u32_e32 v60, v250, v132
	v_lshlrev_b32_sdwa v132, v215, v195 dst_sel:DWORD dst_unused:UNUSED_PAD src0_sel:DWORD src1_sel:WORD_1
	v_add_u32_e32 v64, v250, v132
	global_load_dwordx4 v[52:55], v52, s[98:99]
	s_nop 0
	global_load_dwordx4 v[56:59], v56, s[98:99]
	s_nop 0
	global_load_dwordx4 v[60:63], v60, s[98:99]
	s_nop 0
	global_load_dwordx4 v[64:67], v64, s[98:99]
	s_branch .LBB0_1649
